# pool phase: W^T LDS staging skipped for a CU's 2nd-4th item of a layer (same scale group when grid %4==0): removes 4 loads, a full vmcnt(0) drain and 4 ds_writes per item
# speedup vs baseline: 1.0019x; 1.0019x over previous
.LBB0_214:
	s_and_b32 s98, s58, 3
	s_cmp_lg_u32 s98, 0
	s_cbranch_scc1 .Lpw_copy0
	s_cmp_ge_u32 s93, s58
	s_cbranch_scc1 .Lpw_skip0

.Lpw_skip0:
.LBB0_215:
	s_or_b64 exec, exec, s[84:85]
	s_waitcnt vmcnt(38)
	v_cndmask_b32_e64 v4, 0, v4, s[8:9]
	s_waitcnt vmcnt(37)
	v_cndmask_b32_e64 v5, 0, v5, s[10:11]
	v_lshlrev_b32_e32 v71, 16, v4
	v_and_b32_e32 v72, 0xffff0000, v4
	s_waitcnt vmcnt(28)
	v_cndmask_b32_e64 v70, 0, v51, s[2:3]
	v_cndmask_b32_e64 v7, 0, v7, s[12:13]
	v_add_f32_e32 v51, 0, v71
	v_add_f32_e32 v4, 0, v72
	v_lshlrev_b32_e32 v73, 16, v5
	v_and_b32_e32 v74, 0xffff0000, v5
	v_cndmask_b32_e64 v8, 0, v8, s[14:15]
	v_add_f32_e32 v51, v51, v73
	v_add_f32_e32 v4, v4, v74
	v_lshlrev_b32_e32 v75, 16, v7
	v_and_b32_e32 v76, 0xffff0000, v7
	v_cndmask_b32_e64 v10, 0, v10, s[16:17]
	v_add_f32_e32 v5, v51, v75
	v_add_f32_e32 v4, v4, v76
	v_lshlrev_b32_e32 v77, 16, v8
	v_and_b32_e32 v78, 0xffff0000, v8
	v_cndmask_b32_e64 v11, 0, v11, s[18:19]
	v_add_f32_e32 v5, v5, v77
	v_add_f32_e32 v4, v4, v78
	v_lshlrev_b32_e32 v79, 16, v10
	v_and_b32_e32 v80, 0xffff0000, v10
	v_cndmask_b32_e64 v13, 0, v13, s[20:21]
	v_add_f32_e32 v5, v5, v79
	v_add_f32_e32 v4, v4, v80
	v_lshlrev_b32_e32 v81, 16, v11
	v_and_b32_e32 v103, 0xffff0000, v11
	s_waitcnt vmcnt(27)
	v_cndmask_b32_e64 v69, 0, v52, s[6:7]
	v_cndmask_b32_e64 v14, 0, v14, s[22:23]
	v_add_f32_e32 v5, v5, v81
	v_add_f32_e32 v4, v4, v103
	v_lshlrev_b32_e32 v104, 16, v13
	v_and_b32_e32 v105, 0xffff0000, v13
	s_waitcnt vmcnt(8)
	v_cndmask_b32_e64 v0, 0, v65, s[62:63]
	v_cndmask_b32_e64 v65, 0, v57, s[68:69]
	v_cndmask_b32_e64 v66, 0, v56, s[28:29]
	v_cndmask_b32_e32 v16, 0, v16, vcc
	v_add_f32_e32 v5, v5, v104
	v_add_f32_e32 v4, v4, v105
	v_lshlrev_b32_e32 v56, 16, v14
	v_and_b32_e32 v57, 0xffff0000, v14
	v_lshlrev_b32_e32 v13, 16, v69
	v_and_b32_e32 v14, 0xffff0000, v69
	v_add_u32_e32 v69, s95, v83
	v_cndmask_b32_e64 v67, 0, v54, s[26:27]
	v_cndmask_b32_e64 v68, 0, v53, s[24:25]
	v_cndmask_b32_e64 v17, 0, v17, s[0:1]
	v_add_f32_e32 v5, v5, v56
	v_add_f32_e32 v4, v4, v57
	v_lshlrev_b32_e32 v53, 16, v16
	v_and_b32_e32 v54, 0xffff0000, v16
	v_min_i32_e32 v69, 15, v69
	v_add_f32_e32 v5, v5, v53
	v_add_f32_e32 v4, v4, v54
	v_lshlrev_b32_e32 v51, 16, v17
	v_and_b32_e32 v52, 0xffff0000, v17
	v_add_u32_e32 v69, 1, v69
	v_add_f32_e32 v5, v5, v51
	v_add_f32_e32 v4, v4, v52
	v_lshlrev_b32_e32 v16, 16, v70
	v_and_b32_e32 v17, 0xffff0000, v70
	v_cvt_f32_i32_e32 v69, v69
	v_add_f32_e32 v5, v5, v16
	v_add_f32_e32 v4, v4, v17
	v_add_f32_e32 v5, v5, v13
	v_add_f32_e32 v4, v4, v14
	v_lshlrev_b32_e32 v10, 16, v68
	v_and_b32_e32 v11, 0xffff0000, v68
	v_add_f32_e32 v5, v5, v10
	v_add_f32_e32 v4, v4, v11
	v_lshlrev_b32_e32 v7, 16, v67
	v_and_b32_e32 v8, 0xffff0000, v67
	v_add_f32_e32 v5, v5, v7
	v_add_f32_e32 v67, v4, v8
	v_lshlrev_b32_e32 v4, 16, v66
	v_rcp_iflag_f32_e32 v69, v69
	v_add_f32_e32 v68, v5, v4
	v_and_b32_e32 v5, 0xffff0000, v66
	v_add_f32_e32 v66, v67, v5
	v_lshlrev_b32_e32 v67, 16, v65
	v_and_b32_e32 v65, 0xffff0000, v65
	v_add_f32_e32 v66, v66, v65
	v_add_f32_e32 v68, v68, v67
	v_fma_f32 v65, v69, v66, -v65
	v_fma_f32 v67, v69, v68, -v67
	v_cvt_pk_bf16_f32 v65, v67, v65
	v_add_u32_e32 v116, 0, v145
	s_waitcnt lgkmcnt(0)
	s_barrier
	ds_write_b32 v116, v65 offset:34816
	v_sub_f32_e32 v65, v68, v71
	v_add_u32_e32 v68, s95, v127
	v_min_i32_e32 v68, 15, v68
	v_add_u32_e32 v68, 1, v68
	v_cvt_f32_i32_e32 v68, v68
	v_cndmask_b32_e64 v59, v59, 0, s[34:35]
	v_sub_f32_e32 v66, v66, v72
	v_lshlrev_b32_e32 v67, 16, v59
	v_rcp_iflag_f32_e32 v68, v68
	v_and_b32_e32 v59, 0xffff0000, v59
	v_add_f32_e32 v65, v65, v67
	v_add_f32_e32 v66, v66, v59
	v_fma_f32 v67, v68, v65, -v67
	v_fma_f32 v59, v68, v66, -v59
	v_cvt_pk_bf16_f32 v59, v67, v59
	v_add_u32_e32 v67, s95, v128
	v_min_i32_e32 v67, 15, v67
	v_add_u32_e32 v67, 1, v67
	v_cvt_f32_i32_e32 v67, v67
	v_cndmask_b32_e64 v60, 0, v60, s[36:37]
	v_add_u32_e32 v117, 0, v146
	ds_write_b32 v117, v59 offset:34816
	v_rcp_iflag_f32_e32 v67, v67
	v_sub_f32_e32 v59, v65, v73
	v_sub_f32_e32 v65, v66, v74
	v_lshlrev_b32_e32 v66, 16, v60
	v_and_b32_e32 v60, 0xffff0000, v60
	v_add_f32_e32 v59, v59, v66
	v_add_f32_e32 v65, v65, v60
	v_fma_f32 v66, v67, v59, -v66
	v_fma_f32 v60, v67, v65, -v60
	v_cvt_pk_bf16_f32 v60, v66, v60
	v_add_u32_e32 v66, s95, v129
	v_min_i32_e32 v66, 15, v66
	v_add_u32_e32 v66, 1, v66
	v_cvt_f32_i32_e32 v66, v66
	v_cndmask_b32_e64 v61, 0, v61, s[38:39]
	v_add_u32_e32 v168, 0, v147
	ds_write_b32 v168, v60 offset:34816
	v_rcp_iflag_f32_e32 v66, v66
	v_sub_f32_e32 v59, v59, v75
	v_sub_f32_e32 v60, v65, v76
	v_lshlrev_b32_e32 v65, 16, v61
	v_and_b32_e32 v61, 0xffff0000, v61
	v_add_f32_e32 v59, v59, v65
	v_add_f32_e32 v60, v60, v61
	v_fma_f32 v65, v66, v59, -v65
	v_fma_f32 v61, v66, v60, -v61
	v_cvt_pk_bf16_f32 v61, v65, v61
	v_add_u32_e32 v65, s95, v130
	v_min_i32_e32 v65, 15, v65
	v_add_u32_e32 v65, 1, v65
	v_cvt_f32_i32_e32 v65, v65
	v_cndmask_b32_e64 v62, 0, v62, s[40:41]
	v_add_u32_e32 v169, 0, v148
	ds_write_b32 v169, v61 offset:34816
	v_rcp_iflag_f32_e32 v65, v65
	v_sub_f32_e32 v59, v59, v77
	v_lshlrev_b32_e32 v61, 16, v62
	v_sub_f32_e32 v60, v60, v78
	v_and_b32_e32 v62, 0xffff0000, v62
	v_add_f32_e32 v59, v59, v61
	v_add_f32_e32 v60, v60, v62
	v_fma_f32 v61, v65, v59, -v61
	v_cndmask_b32_e64 v63, 0, v63, s[42:43]
	v_fma_f32 v62, v65, v60, -v62
	v_cvt_pk_bf16_f32 v61, v61, v62
	v_add_u32_e32 v170, 0, v149
	ds_write_b32 v170, v61 offset:34816
	v_lshlrev_b32_e32 v61, 16, v63
	v_and_b32_e32 v62, 0xffff0000, v63
	v_add_u32_e32 v63, s95, v131
	v_min_i32_e32 v63, 15, v63
	v_add_u32_e32 v63, 1, v63
	v_cvt_f32_i32_e32 v63, v63
	v_sub_f32_e32 v59, v59, v79
	v_sub_f32_e32 v60, v60, v80
	v_add_f32_e32 v59, v59, v61
	v_rcp_iflag_f32_e32 v63, v63
	v_add_f32_e32 v60, v60, v62
	v_cndmask_b32_e64 v64, 0, v64, s[44:45]
	v_add_u32_e32 v171, 0, v150
	v_fma_f32 v61, v63, v59, -v61
	v_fma_f32 v62, v63, v60, -v62
	v_add_u32_e32 v63, s95, v132
	v_min_i32_e32 v63, 15, v63
	v_add_u32_e32 v63, 1, v63
	v_cvt_f32_i32_e32 v63, v63
	v_cvt_pk_bf16_f32 v61, v61, v62
	ds_write_b32 v171, v61 offset:34816
	v_sub_f32_e32 v59, v59, v81
	v_rcp_iflag_f32_e32 v63, v63
	v_sub_f32_e32 v60, v60, v103
	v_lshlrev_b32_e32 v61, 16, v64
	v_and_b32_e32 v62, 0xffff0000, v64
	v_add_f32_e32 v59, v59, v61
	v_add_f32_e32 v60, v60, v62
	v_fma_f32 v61, v63, v59, -v61
	v_fma_f32 v62, v63, v60, -v62
	v_cvt_pk_bf16_f32 v61, v61, v62
	v_add_u32_e32 v62, s95, v133
	v_min_i32_e32 v62, 15, v62
	v_add_u32_e32 v62, 1, v62
	v_cvt_f32_i32_e32 v62, v62
	v_cndmask_b32_e64 v58, 0, v58, s[46:47]
	v_add_u32_e32 v172, 0, v151
	ds_write_b32 v172, v61 offset:34816
	v_rcp_iflag_f32_e32 v62, v62
	v_sub_f32_e32 v59, v59, v104
	v_lshlrev_b32_e32 v61, 16, v58
	v_add_f32_e32 v59, v59, v61
	v_fma_f32 v61, v62, v59, -v61
	v_sub_f32_e32 v56, v59, v56
	v_add_u32_e32 v59, s95, v134
	v_min_i32_e32 v59, 15, v59
	v_add_u32_e32 v59, 1, v59
	v_cvt_f32_i32_e32 v59, v59
	v_sub_f32_e32 v60, v60, v105
	v_and_b32_e32 v58, 0xffff0000, v58
	v_add_f32_e32 v60, v60, v58
	v_fma_f32 v58, v62, v60, -v58
	v_rcp_iflag_f32_e32 v59, v59
	v_cndmask_b32_e64 v55, 0, v55, s[48:49]
	v_cvt_pk_bf16_f32 v58, v61, v58
	v_add_u32_e32 v173, 0, v152
	ds_write_b32 v173, v58 offset:34816
	v_lshlrev_b32_e32 v58, 16, v55
	v_add_f32_e32 v56, v56, v58
	v_fma_f32 v58, v59, v56, -v58
	v_sub_f32_e32 v53, v56, v53
	v_add_u32_e32 v56, s95, v135
	v_min_i32_e32 v56, 15, v56
	v_add_u32_e32 v56, 1, v56
	v_cvt_f32_i32_e32 v56, v56
	v_sub_f32_e32 v57, v60, v57
	v_and_b32_e32 v55, 0xffff0000, v55
	v_add_f32_e32 v57, v57, v55
	v_fma_f32 v55, v59, v57, -v55
	v_rcp_iflag_f32_e32 v56, v56
	v_cndmask_b32_e64 v50, 0, v50, s[50:51]
	v_cvt_pk_bf16_f32 v55, v58, v55
	v_add_u32_e32 v174, 0, v153
	ds_write_b32 v174, v55 offset:34816
	v_sub_f32_e32 v54, v57, v54
	v_lshlrev_b32_e32 v55, 16, v50
	v_and_b32_e32 v50, 0xffff0000, v50
	v_add_f32_e32 v54, v54, v50
	v_add_f32_e32 v53, v53, v55
	v_fma_f32 v50, v56, v54, -v50
	v_fma_f32 v55, v56, v53, -v55
	v_cvt_pk_bf16_f32 v50, v55, v50
	v_add_u32_e32 v175, 0, v154
	ds_write_b32 v175, v50 offset:34816
	v_sub_f32_e32 v50, v53, v51
	v_add_u32_e32 v53, s95, v136
	v_min_i32_e32 v53, 15, v53
	v_add_u32_e32 v53, 1, v53
	v_cvt_f32_i32_e32 v53, v53
	v_cndmask_b32_e64 v15, 0, v15, s[52:53]
	v_sub_f32_e32 v51, v54, v52
	v_lshlrev_b32_e32 v52, 16, v15
	v_rcp_iflag_f32_e32 v53, v53
	v_and_b32_e32 v15, 0xffff0000, v15
	v_add_f32_e32 v51, v51, v15
	v_add_f32_e32 v50, v50, v52
	v_fma_f32 v15, v53, v51, -v15
	v_fma_f32 v52, v53, v50, -v52
	v_cvt_pk_bf16_f32 v15, v52, v15
	v_add_u32_e32 v176, 0, v155
	ds_write_b32 v176, v15 offset:34816
	v_sub_f32_e32 v15, v50, v16
	v_add_u32_e32 v50, s95, v137
	v_min_i32_e32 v50, 15, v50
	v_add_u32_e32 v50, 1, v50
	v_cvt_f32_i32_e32 v50, v50
	v_cndmask_b32_e64 v12, 0, v12, s[54:55]
	v_sub_f32_e32 v16, v51, v17
	v_lshlrev_b32_e32 v17, 16, v12
	v_rcp_iflag_f32_e32 v50, v50
	v_and_b32_e32 v12, 0xffff0000, v12
	v_add_f32_e32 v16, v16, v12
	v_add_f32_e32 v15, v15, v17
	v_fma_f32 v12, v50, v16, -v12
	v_fma_f32 v17, v50, v15, -v17
	v_cvt_pk_bf16_f32 v12, v17, v12
	v_add_u32_e32 v177, 0, v156
	ds_write_b32 v177, v12 offset:34816
	v_sub_f32_e32 v12, v15, v13
	v_add_u32_e32 v15, s95, v138
	v_min_i32_e32 v15, 15, v15
	v_add_u32_e32 v15, 1, v15
	v_cvt_f32_i32_e32 v15, v15
	v_cndmask_b32_e64 v9, 0, v9, s[56:57]
	v_sub_f32_e32 v13, v16, v14
	v_lshlrev_b32_e32 v14, 16, v9
	v_rcp_iflag_f32_e32 v15, v15
	v_and_b32_e32 v9, 0xffff0000, v9
	v_add_f32_e32 v13, v13, v9
	v_add_f32_e32 v12, v12, v14
	v_fma_f32 v9, v15, v13, -v9
	v_fma_f32 v14, v15, v12, -v14
	v_cvt_pk_bf16_f32 v9, v14, v9
	v_add_u32_e32 v178, 0, v157
	ds_write_b32 v178, v9 offset:34816
	v_sub_f32_e32 v9, v12, v10
	v_add_u32_e32 v12, s95, v139
	v_min_i32_e32 v12, 15, v12
	v_add_u32_e32 v12, 1, v12
	v_cvt_f32_i32_e32 v12, v12
	v_cndmask_b32_e64 v6, 0, v6, s[58:59]
	v_sub_f32_e32 v10, v13, v11
	v_lshlrev_b32_e32 v11, 16, v6
	v_rcp_iflag_f32_e32 v12, v12
	v_and_b32_e32 v6, 0xffff0000, v6
	v_add_f32_e32 v10, v10, v6
	v_add_f32_e32 v9, v9, v11
	v_fma_f32 v6, v12, v10, -v6
	v_fma_f32 v11, v12, v9, -v11
	v_cvt_pk_bf16_f32 v6, v11, v6
	v_add_u32_e32 v179, 0, v158
	ds_write_b32 v179, v6 offset:34816
	v_sub_f32_e32 v6, v9, v7
	v_add_u32_e32 v9, s95, v140
	v_min_i32_e32 v9, 15, v9
	v_add_u32_e32 v9, 1, v9
	v_cvt_f32_i32_e32 v9, v9
	v_cndmask_b32_e64 v3, 0, v3, s[60:61]
	v_sub_f32_e32 v7, v10, v8
	v_lshlrev_b32_e32 v8, 16, v3
	v_rcp_iflag_f32_e32 v9, v9
	v_and_b32_e32 v3, 0xffff0000, v3
	v_add_f32_e32 v7, v7, v3
	v_add_f32_e32 v6, v6, v8
	v_fma_f32 v3, v9, v7, -v3
	v_fma_f32 v8, v9, v6, -v8
	v_cvt_pk_bf16_f32 v3, v8, v3
	v_add_u32_e32 v180, 0, v159
	ds_write_b32 v180, v3 offset:34816
	v_sub_f32_e32 v3, v6, v4
	v_add_u32_e32 v6, s95, v141
	v_min_i32_e32 v6, 15, v6
	v_add_u32_e32 v6, 1, v6
	v_cvt_f32_i32_e32 v6, v6
	v_sub_f32_e32 v4, v7, v5
	v_lshlrev_b32_e32 v5, 16, v0
	v_and_b32_e32 v0, 0xffff0000, v0
	v_rcp_iflag_f32_e32 v6, v6
	s_or_b32 s0, s94, 0x80
	v_add_f32_e32 v3, v3, v5
	v_add_f32_e32 v4, v4, v0
	s_xor_b32 s1, s95, 0xffffff7f
	s_mul_i32 s2, s0, 0x1e00
	v_fma_f32 v3, v6, v3, -v5
	v_fma_f32 v0, v6, v4, -v0
	s_mul_hi_i32 s3, s0, 0x1e00
	s_add_u32 s2, s91, s2
	v_cvt_pk_bf16_f32 v0, v3, v0
	s_addc_u32 s3, s92, s3
	v_mov_b32_e32 v3, v1
	v_add_u32_e32 v181, 0, v160
	v_cmp_lt_i32_e32 vcc, s1, v141
	v_lshl_add_u64 v[2:3], s[2:3], 0, v[2:3]
	s_mov_b64 s[2:3], 0x1720
	ds_write_b32 v181, v0 offset:34816
	v_lshl_add_u64 v[2:3], v[2:3], 0, s[2:3]
	v_cndmask_b32_e32 v0, 0, v141, vcc
	s_movk_i32 s6, 0x1e00
	v_mad_i64_i32 v[4:5], s[2:3], v0, s6, v[2:3]
	global_load_dword v0, v[4:5], off
	v_add_u32_e32 v185, v144, v143
	v_add_u32_e32 v183, v144, v161
	v_lshlrev_b32_e32 v104, 1, v90
	v_mov_b32_e32 v105, v1
	v_mov_b32_e32 v103, v1
	v_add_u32_e32 v184, v144, v163
	v_lshlrev_b32_e32 v114, 1, v98
	v_mov_b32_e32 v115, v1
	v_readlane_b32 s56, v253, 1
	s_mov_b64 s[8:9], 0
	v_readlane_b32 s58, v253, 3
	s_movk_i32 s56, 0x5ff
	s_mov_b32 s61, 0xf800000
	v_readlane_b32 s57, v253, 2
	v_readlane_b32 s59, v253, 4
	s_waitcnt vmcnt(0)
	v_cndmask_b32_e32 v182, 0, v0, vcc
	v_cmp_lt_i32_e32 vcc, s1, v85
	v_mov_b32_e32 v209, 0
	s_nop 0
	v_cndmask_b32_e32 v0, 0, v85, vcc
	v_mad_i64_i32 v[4:5], s[2:3], v0, s6, v[2:3]
	s_and_saveexec_b64 s[98:99], vcc
	global_load_dword v209, v[4:5], off
	s_mov_b64 exec, s[98:99]
	v_cmp_lt_i32_e32 vcc, s1, v91
	v_mov_b32_e32 v211, 0
	s_nop 0
	v_cndmask_b32_e32 v0, 0, v91, vcc
	v_mad_i64_i32 v[4:5], s[2:3], v0, s6, v[2:3]
	s_and_saveexec_b64 s[98:99], vcc
	global_load_dword v211, v[4:5], off
	s_mov_b64 exec, s[98:99]
	v_cmp_lt_i32_e32 vcc, s1, v93
	v_mov_b32_e32 v212, 0
	s_nop 0
	v_cndmask_b32_e32 v0, 0, v93, vcc
	v_mad_i64_i32 v[4:5], s[2:3], v0, s6, v[2:3]
	s_and_saveexec_b64 s[98:99], vcc
	global_load_dword v212, v[4:5], off
	s_mov_b64 exec, s[98:99]
	v_cmp_lt_i32_e32 vcc, s1, v95
	v_mov_b32_e32 v213, 0
	s_nop 0
	v_cndmask_b32_e32 v0, 0, v95, vcc
	v_mad_i64_i32 v[4:5], s[2:3], v0, s6, v[2:3]
	s_and_saveexec_b64 s[98:99], vcc
	global_load_dword v213, v[4:5], off
	s_mov_b64 exec, s[98:99]
	v_cmp_lt_i32_e32 vcc, s1, v97
	v_mov_b32_e32 v214, 0
	s_nop 0
	v_cndmask_b32_e32 v0, 0, v97, vcc
	v_mad_i64_i32 v[4:5], s[2:3], v0, s6, v[2:3]
	s_and_saveexec_b64 s[98:99], vcc
	global_load_dword v214, v[4:5], off
	s_mov_b64 exec, s[98:99]
	v_cmp_lt_i32_e32 vcc, s1, v99
	v_mov_b32_e32 v215, 0
	s_nop 0
	v_cndmask_b32_e32 v0, 0, v99, vcc
	v_mad_i64_i32 v[4:5], s[2:3], v0, s6, v[2:3]
	s_and_saveexec_b64 s[98:99], vcc
	global_load_dword v215, v[4:5], off
	s_mov_b64 exec, s[98:99]
	v_cmp_lt_i32_e32 vcc, s1, v101
	v_mov_b32_e32 v217, 0
	s_nop 0
	v_cndmask_b32_e32 v0, 0, v101, vcc
	v_mad_i64_i32 v[4:5], s[2:3], v0, s6, v[2:3]
	s_and_saveexec_b64 s[98:99], vcc
	global_load_dword v217, v[4:5], off
	s_mov_b64 exec, s[98:99]
	v_cmp_lt_i32_e32 vcc, s1, v119
	v_mov_b32_e32 v218, 0
	s_nop 0
	v_cndmask_b32_e32 v0, 0, v119, vcc
	v_mad_i64_i32 v[4:5], s[2:3], v0, s6, v[2:3]
	s_and_saveexec_b64 s[98:99], vcc
	global_load_dword v218, v[4:5], off
	s_mov_b64 exec, s[98:99]
	v_cmp_lt_i32_e32 vcc, s1, v120
	v_mov_b32_e32 v219, 0
	s_nop 0
	v_cndmask_b32_e32 v0, 0, v120, vcc
	v_mad_i64_i32 v[4:5], s[2:3], v0, s6, v[2:3]
	s_and_saveexec_b64 s[98:99], vcc
	global_load_dword v219, v[4:5], off
	s_mov_b64 exec, s[98:99]
	v_cmp_lt_i32_e32 vcc, s1, v121
	v_mov_b32_e32 v220, 0
	s_nop 0
	v_cndmask_b32_e32 v0, 0, v121, vcc
	v_mad_i64_i32 v[4:5], s[2:3], v0, s6, v[2:3]
	s_and_saveexec_b64 s[98:99], vcc
	global_load_dword v220, v[4:5], off
	s_mov_b64 exec, s[98:99]
	v_cmp_lt_i32_e32 vcc, s1, v122
	v_mov_b32_e32 v221, 0
	s_nop 0
	v_cndmask_b32_e32 v0, 0, v122, vcc
	v_mad_i64_i32 v[4:5], s[2:3], v0, s6, v[2:3]
	s_and_saveexec_b64 s[98:99], vcc
	global_load_dword v221, v[4:5], off
	s_mov_b64 exec, s[98:99]
	v_cmp_lt_i32_e32 vcc, s1, v123
	v_mov_b32_e32 v223, 0
	s_nop 0
	v_cndmask_b32_e32 v0, 0, v123, vcc
	v_mad_i64_i32 v[4:5], s[2:3], v0, s6, v[2:3]
	s_and_saveexec_b64 s[98:99], vcc
	global_load_dword v223, v[4:5], off
	s_mov_b64 exec, s[98:99]
	v_cmp_lt_i32_e32 vcc, s1, v124
	v_mov_b32_e32 v224, 0
	s_nop 0
	v_cndmask_b32_e32 v0, 0, v124, vcc
	v_mad_i64_i32 v[4:5], s[2:3], v0, s6, v[2:3]
	s_and_saveexec_b64 s[98:99], vcc
	global_load_dword v224, v[4:5], off
	s_mov_b64 exec, s[98:99]
	v_cmp_lt_i32_e32 vcc, s1, v125
	v_mov_b32_e32 v225, 0
	s_nop 0
	v_cndmask_b32_e32 v0, 0, v125, vcc
	v_mad_i64_i32 v[4:5], s[2:3], v0, s6, v[2:3]
	s_and_saveexec_b64 s[98:99], vcc
	global_load_dword v225, v[4:5], off
	s_mov_b64 exec, s[98:99]
	v_cmp_lt_i32_e32 vcc, s1, v126
	v_mov_b32_e32 v227, 0
	s_nop 0
	v_cndmask_b32_e32 v0, 0, v126, vcc
	v_mad_i64_i32 v[4:5], s[2:3], v0, s6, v[2:3]
	s_and_saveexec_b64 s[98:99], vcc
	global_load_dword v227, v[4:5], off
	s_mov_b64 exec, s[98:99]
	v_cmp_lt_i32_e32 vcc, s1, v83
	v_mov_b32_e32 v226, 0
	s_nop 0
	v_cndmask_b32_e32 v0, 0, v83, vcc
	v_mad_i64_i32 v[4:5], s[2:3], v0, s6, v[2:3]
	s_and_saveexec_b64 s[98:99], vcc
	global_load_dword v226, v[4:5], off
	s_mov_b64 exec, s[98:99]
	v_cmp_gt_i32_e32 vcc, s1, v83
	s_nop 1
	v_cndmask_b32_e64 v0, v127, 0, vcc
	v_mad_i64_i32 v[4:5], s[2:3], v0, s6, v[2:3]
	global_load_dword v0, v[4:5], off
	s_waitcnt vmcnt(0)
	v_cndmask_b32_e64 v222, v0, 0, vcc
	v_cmp_lt_i32_e32 vcc, s1, v128
	v_mov_b32_e32 v216, 0
	s_nop 0
	v_cndmask_b32_e32 v0, 0, v128, vcc
	v_mad_i64_i32 v[4:5], s[2:3], v0, s6, v[2:3]
	s_and_saveexec_b64 s[98:99], vcc
	global_load_dword v216, v[4:5], off
	s_mov_b64 exec, s[98:99]
	v_cmp_lt_i32_e32 vcc, s1, v129
	v_mov_b32_e32 v210, 0
	s_nop 0
	v_cndmask_b32_e32 v0, 0, v129, vcc
	v_mad_i64_i32 v[4:5], s[2:3], v0, s6, v[2:3]
	s_and_saveexec_b64 s[98:99], vcc
	global_load_dword v210, v[4:5], off
	s_mov_b64 exec, s[98:99]
	v_cmp_lt_i32_e32 vcc, s1, v130
	v_mov_b32_e32 v208, 0
	s_nop 0
	v_cndmask_b32_e32 v0, 0, v130, vcc
	v_mad_i64_i32 v[4:5], s[2:3], v0, s6, v[2:3]
	s_and_saveexec_b64 s[98:99], vcc
	global_load_dword v208, v[4:5], off
	s_mov_b64 exec, s[98:99]
	v_cmp_lt_i32_e32 vcc, s1, v131
	v_mov_b32_e32 v207, 0
	s_nop 0
	v_cndmask_b32_e32 v0, 0, v131, vcc
	v_mad_i64_i32 v[4:5], s[2:3], v0, s6, v[2:3]
	s_and_saveexec_b64 s[98:99], vcc
	global_load_dword v207, v[4:5], off
	s_mov_b64 exec, s[98:99]
	v_cmp_lt_i32_e32 vcc, s1, v132
	v_mov_b32_e32 v206, 0
	s_nop 0
	v_cndmask_b32_e32 v0, 0, v132, vcc
	v_mad_i64_i32 v[4:5], s[2:3], v0, s6, v[2:3]
	s_and_saveexec_b64 s[98:99], vcc
	global_load_dword v206, v[4:5], off
	s_mov_b64 exec, s[98:99]
	v_cmp_lt_i32_e32 vcc, s1, v133
	v_mov_b32_e32 v205, 0
	s_nop 0
	v_cndmask_b32_e32 v0, 0, v133, vcc
	v_mad_i64_i32 v[4:5], s[2:3], v0, s6, v[2:3]
	s_and_saveexec_b64 s[98:99], vcc
	global_load_dword v205, v[4:5], off
	s_mov_b64 exec, s[98:99]
	v_cmp_lt_i32_e32 vcc, s1, v134
	v_mov_b32_e32 v204, 0
	s_nop 0
	v_cndmask_b32_e32 v0, 0, v134, vcc
	v_mad_i64_i32 v[4:5], s[2:3], v0, s6, v[2:3]
	s_and_saveexec_b64 s[98:99], vcc
	global_load_dword v204, v[4:5], off
	s_mov_b64 exec, s[98:99]
	v_cmp_lt_i32_e32 vcc, s1, v135
	v_mov_b32_e32 v192, 0
	s_nop 0
	v_cndmask_b32_e32 v0, 0, v135, vcc
	v_mad_i64_i32 v[4:5], s[2:3], v0, s6, v[2:3]
	s_and_saveexec_b64 s[98:99], vcc
	global_load_dword v192, v[4:5], off
	s_mov_b64 exec, s[98:99]
	v_cmp_lt_i32_e32 vcc, s1, v136
	v_mov_b32_e32 v190, 0
	s_nop 0
	v_cndmask_b32_e32 v0, 0, v136, vcc
	v_mad_i64_i32 v[4:5], s[2:3], v0, s6, v[2:3]
	s_and_saveexec_b64 s[98:99], vcc
	global_load_dword v190, v[4:5], off
	s_mov_b64 exec, s[98:99]
	v_cmp_lt_i32_e32 vcc, s1, v137
	v_mov_b32_e32 v189, 0
	s_nop 0
	v_cndmask_b32_e32 v0, 0, v137, vcc
	v_mad_i64_i32 v[4:5], s[2:3], v0, s6, v[2:3]
	s_and_saveexec_b64 s[98:99], vcc
	global_load_dword v189, v[4:5], off
	s_mov_b64 exec, s[98:99]
	v_cmp_lt_i32_e32 vcc, s1, v138
	v_mov_b32_e32 v188, 0
	s_nop 0
	v_cndmask_b32_e32 v0, 0, v138, vcc
	v_mad_i64_i32 v[4:5], s[2:3], v0, s6, v[2:3]
	s_and_saveexec_b64 s[98:99], vcc
	global_load_dword v188, v[4:5], off
	s_mov_b64 exec, s[98:99]
	v_cmp_lt_i32_e32 vcc, s1, v139
	v_mov_b32_e32 v187, 0
	s_nop 0
	v_cndmask_b32_e32 v0, 0, v139, vcc
	v_mad_i64_i32 v[4:5], s[2:3], v0, s6, v[2:3]
	s_and_saveexec_b64 s[98:99], vcc
	global_load_dword v187, v[4:5], off
	s_mov_b64 exec, s[98:99]
	v_cmp_lt_i32_e32 vcc, s1, v140
	s_and_b32 s1, s0, 0xf80
	s_nop 0
	v_cndmask_b32_e32 v0, 0, v140, vcc
	v_mad_i64_i32 v[2:3], s[2:3], v0, s6, v[2:3]
	global_load_dword v0, v[2:3], off
	v_add_u32_e32 v2, s94, v142
	v_ashrrev_i32_e32 v3, 31, v2
	v_lshlrev_b64 v[2:3], 12, v[2:3]
	s_waitcnt lgkmcnt(0)
	s_barrier
	v_lshl_add_u64 v[2:3], s[70:71], 0, v[2:3]
	s_mov_b64 s[2:3], 0x26000b00
	ds_read_b128 v[74:77], v185 offset:34816
	ds_read_b128 v[78:81], v185 offset:34848
	ds_read_b128 v[70:73], v185 offset:34880
	ds_read_b128 v[66:69], v185 offset:34912
	ds_read_b128 v[62:65], v185 offset:34944
	ds_read_b128 v[58:61], v185 offset:34976
	ds_read_b128 v[54:57], v185 offset:35008
	ds_read_b128 v[50:53], v185 offset:35040
	v_lshl_add_u64 v[106:107], v[2:3], 0, s[2:3]
	ds_read_b128 v[2:5], v183
	ds_read_b128 v[108:111], v183 offset:32
	ds_read_b128 v[228:231], v183 offset:64
	ds_read_b128 v[242:245], v183 offset:96
	s_waitcnt lgkmcnt(3)
	v_mfma_f32_32x32x16_bf16 v[2:17], v[2:5], v[74:77], 0
	s_waitcnt vmcnt(0)
	v_cndmask_b32_e32 v186, 0, v0, vcc
	s_waitcnt lgkmcnt(2)
	v_mfma_f32_32x32x16_bf16 v[2:17], v[108:111], v[78:81], v[2:17]
	ds_read_b128 v[108:111], v183 offset:128
	s_waitcnt lgkmcnt(2)
	v_mfma_f32_32x32x16_bf16 v[2:17], v[228:231], v[70:73], v[2:17]
	ds_read_b128 v[228:231], v183 offset:160
	s_waitcnt lgkmcnt(2)
	v_mfma_f32_32x32x16_bf16 v[2:17], v[242:245], v[66:69], v[2:17]
	ds_read_b128 v[242:245], v183 offset:192
	s_waitcnt lgkmcnt(2)
	v_mfma_f32_32x32x16_bf16 v[2:17], v[108:111], v[62:65], v[2:17]
	ds_read_b128 v[108:111], v183 offset:224
	s_waitcnt lgkmcnt(2)
	v_mfma_f32_32x32x16_bf16 v[2:17], v[228:231], v[58:61], v[2:17]
	s_waitcnt lgkmcnt(1)
	v_mfma_f32_32x32x16_bf16 v[2:17], v[242:245], v[54:57], v[2:17]
	s_waitcnt lgkmcnt(0)
	v_mfma_f32_32x32x16_bf16 v[2:17], v[108:111], v[50:53], v[2:17]
	v_lshlrev_b32_e32 v108, 1, v92
	v_mov_b32_e32 v109, v1
	s_nop 9
	v_mul_f32_e32 v0, v46, v2
	v_mul_f32_e32 v2, v47, v3
	v_cvt_pk_bf16_f32 v2, v0, v2
	v_mul_f32_e32 v0, v48, v4
	v_mul_f32_e32 v3, v49, v5
	v_cvt_pk_bf16_f32 v3, v0, v3
	v_lshlrev_b32_e32 v0, 1, v88
	v_lshl_add_u64 v[4:5], v[106:107], 0, v[0:1]
	global_store_dwordx2 v[4:5], v[2:3], off
	v_mul_f32_e32 v2, v42, v6
	v_mul_f32_e32 v3, v43, v7
	v_cvt_pk_bf16_f32 v2, v2, v3
	v_mul_f32_e32 v3, v44, v8
	v_mul_f32_e32 v4, v45, v9
	v_cvt_pk_bf16_f32 v3, v3, v4
	v_lshl_add_u64 v[4:5], v[106:107], 0, v[104:105]
	global_store_dwordx2 v[4:5], v[2:3], off
	v_mul_f32_e32 v2, v38, v10
	v_mul_f32_e32 v3, v39, v11
	v_cvt_pk_bf16_f32 v2, v2, v3
	v_mul_f32_e32 v3, v40, v12
	v_mul_f32_e32 v4, v41, v13
	v_cvt_pk_bf16_f32 v3, v3, v4
	v_lshl_add_u64 v[4:5], v[106:107], 0, v[108:109]
	global_store_dwordx2 v[4:5], v[2:3], off
	v_mul_f32_e32 v2, v34, v14
	v_mul_f32_e32 v3, v35, v15
	v_cvt_pk_bf16_f32 v2, v2, v3
	v_mul_f32_e32 v3, v36, v16
	v_mul_f32_e32 v4, v37, v17
	v_cvt_pk_bf16_f32 v3, v3, v4
	v_lshl_add_u64 v[4:5], v[106:107], 0, v[102:103]
	global_store_dwordx2 v[4:5], v[2:3], off
	ds_read_b128 v[228:231], v184
	ds_read_b128 v[242:245], v184 offset:32
	ds_read_b128 v[246:249], v184 offset:64
	s_waitcnt lgkmcnt(2)
	v_mfma_f32_32x32x16_bf16 v[2:17], v[228:231], v[74:77], 0
	ds_read_b128 v[228:231], v184 offset:96
	s_waitcnt lgkmcnt(2)
	v_mfma_f32_32x32x16_bf16 v[2:17], v[242:245], v[78:81], v[2:17]
	ds_read_b128 v[242:245], v184 offset:128
	v_lshlrev_b32_e32 v110, 1, v94
	v_mov_b32_e32 v111, v1
	v_lshlrev_b32_e32 v112, 1, v96
	v_mov_b32_e32 v113, v1
	s_waitcnt lgkmcnt(2)
	v_mfma_f32_32x32x16_bf16 v[2:17], v[246:249], v[70:73], v[2:17]
	ds_read_b128 v[246:249], v184 offset:160
	s_waitcnt lgkmcnt(2)
	v_mfma_f32_32x32x16_bf16 v[2:17], v[228:231], v[66:69], v[2:17]
	ds_read_b128 v[228:231], v184 offset:192
	s_waitcnt lgkmcnt(2)
	v_mfma_f32_32x32x16_bf16 v[2:17], v[242:245], v[62:65], v[2:17]
	ds_read_b128 v[242:245], v184 offset:224
	v_add_u32_e32 v68, s1, v83
	v_min_i32_e32 v68, 15, v68
	v_add_u32_e32 v68, 1, v68
	v_cvt_f32_i32_e32 v68, v68
	v_lshlrev_b32_e32 v66, 16, v226
	v_and_b32_e32 v67, 0xffff0000, v226
	s_waitcnt lgkmcnt(2)
	v_mfma_f32_32x32x16_bf16 v[2:17], v[246:249], v[58:61], v[2:17]
	v_lshlrev_b32_e32 v62, 16, v217
	v_and_b32_e32 v63, 0xffff0000, v217
	v_rcp_iflag_f32_e32 v68, v68
	s_waitcnt lgkmcnt(1)
	v_mfma_f32_32x32x16_bf16 v[2:17], v[228:231], v[54:57], v[2:17]
	v_lshlrev_b32_e32 v58, 16, v214
	v_and_b32_e32 v59, 0xffff0000, v214
	v_lshlrev_b32_e32 v60, 16, v215
	v_and_b32_e32 v61, 0xffff0000, v215
	s_waitcnt lgkmcnt(0)
	v_mfma_f32_32x32x16_bf16 v[2:17], v[242:245], v[50:53], v[2:17]
	v_lshlrev_b32_e32 v50, 16, v209
	v_and_b32_e32 v51, 0xffff0000, v209
	v_lshlrev_b32_e32 v52, 16, v211
	v_and_b32_e32 v53, 0xffff0000, v211
	v_lshlrev_b32_e32 v54, 16, v212
	v_and_b32_e32 v55, 0xffff0000, v212
	v_lshlrev_b32_e32 v56, 16, v213
	s_nop 4
	v_mul_f32_e32 v2, v30, v2
	v_mul_f32_e32 v3, v31, v3
	v_cvt_pk_bf16_f32 v2, v2, v3
	v_mul_f32_e32 v3, v32, v4
	v_mul_f32_e32 v4, v33, v5
	v_cvt_pk_bf16_f32 v3, v3, v4
	v_lshl_add_u64 v[4:5], v[106:107], 0, v[110:111]
	global_store_dwordx2 v[4:5], v[2:3], off
	v_mul_f32_e32 v2, v26, v6
	v_mul_f32_e32 v3, v27, v7
	v_cvt_pk_bf16_f32 v2, v2, v3
	v_mul_f32_e32 v3, v28, v8
	v_mul_f32_e32 v4, v29, v9
	v_cvt_pk_bf16_f32 v3, v3, v4
	v_lshl_add_u64 v[4:5], v[106:107], 0, v[112:113]
	global_store_dwordx2 v[4:5], v[2:3], off
	v_mul_f32_e32 v2, v22, v10
	v_mul_f32_e32 v3, v23, v11
	v_cvt_pk_bf16_f32 v2, v2, v3
	v_mul_f32_e32 v3, v24, v12
	v_mul_f32_e32 v4, v25, v13
	v_cvt_pk_bf16_f32 v3, v3, v4
	v_lshl_add_u64 v[4:5], v[106:107], 0, v[114:115]
	global_store_dwordx2 v[4:5], v[2:3], off
	v_mul_f32_e32 v2, v18, v14
	v_mul_f32_e32 v3, v19, v15
	v_cvt_pk_bf16_f32 v2, v2, v3
	v_mul_f32_e32 v3, v20, v16
	v_mul_f32_e32 v4, v21, v17
	v_cvt_pk_bf16_f32 v3, v3, v4
	v_lshlrev_b32_e32 v4, 1, v100
	v_mov_b32_e32 v5, v1
	v_lshl_add_u64 v[4:5], v[106:107], 0, v[4:5]
	global_store_dwordx2 v[4:5], v[2:3], off
	v_add_f32_e32 v2, 0, v50
	v_add_f32_e32 v3, 0, v51
	v_add_f32_e32 v2, v2, v52
	v_add_f32_e32 v3, v3, v53
	v_add_f32_e32 v2, v2, v54
	v_add_f32_e32 v3, v3, v55
	v_add_f32_e32 v2, v2, v56
	v_and_b32_e32 v57, 0xffff0000, v213
	v_add_f32_e32 v3, v3, v57
	v_add_f32_e32 v2, v2, v58
	v_add_f32_e32 v3, v3, v59
	v_add_f32_e32 v2, v2, v60
	v_add_f32_e32 v3, v3, v61
	v_add_f32_e32 v2, v2, v62
	v_lshlrev_b32_e32 v16, 16, v218
	v_add_f32_e32 v3, v3, v63
	v_add_f32_e32 v2, v2, v16
	v_and_b32_e32 v17, 0xffff0000, v218
	v_lshlrev_b32_e32 v14, 16, v219
	v_add_f32_e32 v3, v3, v17
	v_add_f32_e32 v2, v2, v14
	v_and_b32_e32 v15, 0xffff0000, v219
	v_lshlrev_b32_e32 v12, 16, v220
	v_add_f32_e32 v3, v3, v15
	v_add_f32_e32 v2, v2, v12
	v_and_b32_e32 v13, 0xffff0000, v220
	v_lshlrev_b32_e32 v10, 16, v221
	v_add_f32_e32 v3, v3, v13
	v_add_f32_e32 v2, v2, v10
	v_and_b32_e32 v11, 0xffff0000, v221
	v_lshlrev_b32_e32 v8, 16, v223
	v_add_f32_e32 v3, v3, v11
	v_add_f32_e32 v2, v2, v8
	v_and_b32_e32 v9, 0xffff0000, v223
	v_lshlrev_b32_e32 v6, 16, v224
	v_add_f32_e32 v3, v3, v9
	v_add_f32_e32 v2, v2, v6
	v_and_b32_e32 v7, 0xffff0000, v224
	v_lshlrev_b32_e32 v4, 16, v225
	v_add_f32_e32 v3, v3, v7
	v_add_f32_e32 v64, v2, v4
	v_and_b32_e32 v5, 0xffff0000, v225
	v_lshlrev_b32_e32 v2, 16, v227
	v_add_f32_e32 v65, v3, v5
	v_add_f32_e32 v64, v64, v2
	v_and_b32_e32 v3, 0xffff0000, v227
	v_add_f32_e32 v65, v65, v3
	v_add_f32_e32 v64, v64, v66
	v_add_f32_e32 v65, v65, v67
	v_fma_f32 v66, v68, v64, -v66
	v_fma_f32 v67, v68, v65, -v67
	v_cvt_pk_bf16_f32 v66, v66, v67
	s_waitcnt lgkmcnt(0)
	s_barrier
	ds_write_b32 v116, v66 offset:34816
	v_add_u32_e32 v66, s1, v127
	v_min_i32_e32 v66, 15, v66
	v_add_u32_e32 v66, 1, v66
	v_cvt_f32_i32_e32 v66, v66
	v_sub_f32_e32 v50, v64, v50
	v_lshlrev_b32_e32 v64, 16, v222
	v_sub_f32_e32 v51, v65, v51
	v_rcp_iflag_f32_e32 v66, v66
	v_and_b32_e32 v65, 0xffff0000, v222
	v_add_f32_e32 v50, v50, v64
	v_add_f32_e32 v51, v51, v65
	v_fma_f32 v64, v66, v50, -v64
	v_fma_f32 v65, v66, v51, -v65
	v_cvt_pk_bf16_f32 v64, v64, v65
	ds_write_b32 v117, v64 offset:34816
	v_add_u32_e32 v64, s1, v128
	v_min_i32_e32 v64, 15, v64
	v_add_u32_e32 v64, 1, v64
	v_cvt_f32_i32_e32 v64, v64
	v_sub_f32_e32 v50, v50, v52
	v_lshlrev_b32_e32 v52, 16, v216
	v_add_f32_e32 v50, v50, v52
	v_rcp_iflag_f32_e32 v64, v64
	v_sub_f32_e32 v51, v51, v53
	v_and_b32_e32 v53, 0xffff0000, v216
	v_add_f32_e32 v51, v51, v53
	v_fma_f32 v52, v64, v50, -v52
	v_sub_f32_e32 v50, v50, v54
	v_add_u32_e32 v54, s1, v129
	v_min_i32_e32 v54, 15, v54
	v_add_u32_e32 v54, 1, v54
	v_cvt_f32_i32_e32 v54, v54
	v_fma_f32 v53, v64, v51, -v53
	v_cvt_pk_bf16_f32 v52, v52, v53
	ds_write_b32 v168, v52 offset:34816
	v_rcp_iflag_f32_e32 v54, v54
	v_sub_f32_e32 v51, v51, v55
	v_lshlrev_b32_e32 v52, 16, v210
	v_and_b32_e32 v53, 0xffff0000, v210
	v_add_f32_e32 v50, v50, v52
	v_add_f32_e32 v51, v51, v53
	v_fma_f32 v52, v54, v50, -v52
	v_fma_f32 v53, v54, v51, -v53
	v_add_u32_e32 v54, s1, v130
	v_min_i32_e32 v54, 15, v54
	v_add_u32_e32 v54, 1, v54
	v_cvt_f32_i32_e32 v54, v54
	v_cvt_pk_bf16_f32 v52, v52, v53
	ds_write_b32 v169, v52 offset:34816
	v_sub_f32_e32 v50, v50, v56
	v_rcp_iflag_f32_e32 v54, v54
	v_sub_f32_e32 v51, v51, v57
	v_lshlrev_b32_e32 v52, 16, v208
	v_and_b32_e32 v53, 0xffff0000, v208
	v_add_f32_e32 v50, v50, v52
	v_add_f32_e32 v51, v51, v53
	v_fma_f32 v52, v54, v50, -v52
	v_fma_f32 v53, v54, v51, -v53
	v_add_u32_e32 v54, s1, v131
	v_min_i32_e32 v54, 15, v54
	v_add_u32_e32 v54, 1, v54
	v_cvt_f32_i32_e32 v54, v54
	v_cvt_pk_bf16_f32 v52, v52, v53
	ds_write_b32 v170, v52 offset:34816
	v_sub_f32_e32 v50, v50, v58
	v_rcp_iflag_f32_e32 v54, v54
	v_sub_f32_e32 v51, v51, v59
	v_lshlrev_b32_e32 v52, 16, v207
	v_and_b32_e32 v53, 0xffff0000, v207
	v_add_f32_e32 v50, v50, v52
	v_add_f32_e32 v51, v51, v53
	v_fma_f32 v52, v54, v50, -v52
	v_fma_f32 v53, v54, v51, -v53
	v_add_u32_e32 v54, s1, v132
	v_min_i32_e32 v54, 15, v54
	v_add_u32_e32 v54, 1, v54
	v_cvt_f32_i32_e32 v54, v54
	v_cvt_pk_bf16_f32 v52, v52, v53
	ds_write_b32 v171, v52 offset:34816
	v_sub_f32_e32 v50, v50, v60
	v_rcp_iflag_f32_e32 v54, v54
	v_sub_f32_e32 v51, v51, v61
	v_lshlrev_b32_e32 v52, 16, v206
	v_and_b32_e32 v53, 0xffff0000, v206
	v_add_f32_e32 v50, v50, v52
	v_add_f32_e32 v51, v51, v53
	v_fma_f32 v52, v54, v50, -v52
	v_fma_f32 v53, v54, v51, -v53
	v_add_u32_e32 v54, s1, v133
	v_min_i32_e32 v54, 15, v54
	v_add_u32_e32 v54, 1, v54
	v_cvt_f32_i32_e32 v54, v54
	v_cvt_pk_bf16_f32 v52, v52, v53
	ds_write_b32 v172, v52 offset:34816
	v_sub_f32_e32 v50, v50, v62
	v_rcp_iflag_f32_e32 v54, v54
	v_lshlrev_b32_e32 v52, 16, v205
	v_sub_f32_e32 v51, v51, v63
	v_and_b32_e32 v53, 0xffff0000, v205
	v_add_f32_e32 v50, v50, v52
	v_add_f32_e32 v51, v51, v53
	v_fma_f32 v52, v54, v50, -v52
	v_fma_f32 v53, v54, v51, -v53
	v_cvt_pk_bf16_f32 v52, v52, v53
	ds_write_b32 v173, v52 offset:34816
	v_add_u32_e32 v52, s1, v134
	v_min_i32_e32 v52, 15, v52
	v_add_u32_e32 v52, 1, v52
	v_cvt_f32_i32_e32 v52, v52
	v_sub_f32_e32 v16, v50, v16
	v_lshlrev_b32_e32 v50, 16, v204
	v_sub_f32_e32 v17, v51, v17
	v_rcp_iflag_f32_e32 v52, v52
	v_and_b32_e32 v51, 0xffff0000, v204
	v_add_f32_e32 v16, v16, v50
	v_add_f32_e32 v17, v17, v51
	v_fma_f32 v50, v52, v16, -v50
	v_fma_f32 v51, v52, v17, -v51
	v_cvt_pk_bf16_f32 v50, v50, v51
	ds_write_b32 v174, v50 offset:34816
	v_add_u32_e32 v50, s1, v135
	v_min_i32_e32 v50, 15, v50
	v_add_u32_e32 v50, 1, v50
	v_cvt_f32_i32_e32 v50, v50
	v_sub_f32_e32 v14, v16, v14
	v_lshlrev_b32_e32 v16, 16, v192
	v_sub_f32_e32 v15, v17, v15
	v_rcp_iflag_f32_e32 v50, v50
	v_and_b32_e32 v17, 0xffff0000, v192
	v_add_f32_e32 v14, v14, v16
	v_add_f32_e32 v15, v15, v17
	v_fma_f32 v16, v50, v14, -v16
	v_fma_f32 v17, v50, v15, -v17
	v_cvt_pk_bf16_f32 v16, v16, v17
	ds_write_b32 v175, v16 offset:34816
	v_add_u32_e32 v16, s1, v136
	v_min_i32_e32 v16, 15, v16
	v_add_u32_e32 v16, 1, v16
	v_cvt_f32_i32_e32 v16, v16
	v_sub_f32_e32 v12, v14, v12
	v_lshlrev_b32_e32 v14, 16, v190
	v_sub_f32_e32 v13, v15, v13
	v_rcp_iflag_f32_e32 v16, v16
	v_and_b32_e32 v15, 0xffff0000, v190
	v_add_f32_e32 v12, v12, v14
	v_add_f32_e32 v13, v13, v15
	v_fma_f32 v14, v16, v12, -v14
	v_fma_f32 v15, v16, v13, -v15
	v_cvt_pk_bf16_f32 v14, v14, v15
	ds_write_b32 v176, v14 offset:34816
	v_add_u32_e32 v14, s1, v137
	v_min_i32_e32 v14, 15, v14
	v_add_u32_e32 v14, 1, v14
	v_cvt_f32_i32_e32 v14, v14
	v_sub_f32_e32 v10, v12, v10
	v_lshlrev_b32_e32 v12, 16, v189
	v_sub_f32_e32 v11, v13, v11
	v_rcp_iflag_f32_e32 v14, v14
	v_and_b32_e32 v13, 0xffff0000, v189
	v_add_f32_e32 v10, v10, v12
	v_add_f32_e32 v11, v11, v13
	v_fma_f32 v12, v14, v10, -v12
	v_fma_f32 v13, v14, v11, -v13
	v_cvt_pk_bf16_f32 v12, v12, v13
	ds_write_b32 v177, v12 offset:34816
	v_add_u32_e32 v12, s1, v138
	v_min_i32_e32 v12, 15, v12
	v_add_u32_e32 v12, 1, v12
	v_cvt_f32_i32_e32 v12, v12
	v_sub_f32_e32 v8, v10, v8
	v_lshlrev_b32_e32 v10, 16, v188
	v_sub_f32_e32 v9, v11, v9
	v_rcp_iflag_f32_e32 v12, v12
	v_and_b32_e32 v11, 0xffff0000, v188
	v_add_f32_e32 v8, v8, v10
	v_add_f32_e32 v9, v9, v11
	v_fma_f32 v10, v12, v8, -v10
	v_fma_f32 v11, v12, v9, -v11
	v_cvt_pk_bf16_f32 v10, v10, v11
	ds_write_b32 v178, v10 offset:34816
	v_add_u32_e32 v10, s1, v139
	v_min_i32_e32 v10, 15, v10
	v_add_u32_e32 v10, 1, v10
	v_cvt_f32_i32_e32 v10, v10
	v_sub_f32_e32 v6, v8, v6
	v_lshlrev_b32_e32 v8, 16, v187
	v_sub_f32_e32 v7, v9, v7
	v_rcp_iflag_f32_e32 v10, v10
	v_and_b32_e32 v9, 0xffff0000, v187
	v_add_f32_e32 v6, v6, v8
	v_add_f32_e32 v7, v7, v9
	v_fma_f32 v8, v10, v6, -v8
	v_fma_f32 v9, v10, v7, -v9
	v_cvt_pk_bf16_f32 v8, v8, v9
	ds_write_b32 v179, v8 offset:34816
	v_add_u32_e32 v8, s1, v140
	v_min_i32_e32 v8, 15, v8
	v_add_u32_e32 v8, 1, v8
	v_cvt_f32_i32_e32 v8, v8
	v_sub_f32_e32 v4, v6, v4
	v_lshlrev_b32_e32 v6, 16, v186
	v_sub_f32_e32 v5, v7, v5
	v_rcp_iflag_f32_e32 v8, v8
	v_and_b32_e32 v7, 0xffff0000, v186
	v_add_f32_e32 v4, v4, v6
	v_add_f32_e32 v5, v5, v7
	v_fma_f32 v6, v8, v4, -v6
	v_fma_f32 v7, v8, v5, -v7
	v_cvt_pk_bf16_f32 v6, v6, v7
	ds_write_b32 v180, v6 offset:34816
	v_add_u32_e32 v6, s1, v141
	v_min_i32_e32 v6, 15, v6
	v_add_u32_e32 v6, 1, v6
	v_cvt_f32_i32_e32 v6, v6
	v_sub_f32_e32 v2, v4, v2
	v_lshlrev_b32_e32 v4, 16, v182
	v_sub_f32_e32 v3, v5, v3
	v_rcp_iflag_f32_e32 v6, v6
	v_and_b32_e32 v5, 0xffff0000, v182
	v_add_f32_e32 v2, v2, v4
	v_add_f32_e32 v3, v3, v5
	v_fma_f32 v2, v6, v2, -v4
	v_fma_f32 v3, v6, v3, -v5
	v_cvt_pk_bf16_f32 v2, v2, v3
	ds_write_b32 v181, v2 offset:34816
	v_add_u32_e32 v2, s0, v142
	v_ashrrev_i32_e32 v3, 31, v2
	v_lshlrev_b64 v[2:3], 12, v[2:3]
	s_waitcnt lgkmcnt(0)
	s_barrier
	v_lshl_add_u64 v[2:3], s[70:71], 0, v[2:3]
	ds_read_b128 v[74:77], v185 offset:34816
	ds_read_b128 v[78:81], v185 offset:34848
	ds_read_b128 v[70:73], v185 offset:34880
	ds_read_b128 v[66:69], v185 offset:34912
	ds_read_b128 v[62:65], v185 offset:34944
	ds_read_b128 v[58:61], v185 offset:34976
	ds_read_b128 v[54:57], v185 offset:35008
	ds_read_b128 v[50:53], v185 offset:35040
	v_lshl_add_u64 v[106:107], v[2:3], 0, s[2:3]
	ds_read_b128 v[2:5], v183
	ds_read_b128 v[168:171], v183 offset:32
	ds_read_b128 v[228:231], v183 offset:64
	ds_read_b128 v[242:245], v183 offset:96
	s_waitcnt lgkmcnt(3)
	v_mfma_f32_32x32x16_bf16 v[2:17], v[2:5], v[74:77], 0
	s_waitcnt lgkmcnt(2)
	v_mfma_f32_32x32x16_bf16 v[2:17], v[168:171], v[78:81], v[2:17]
	ds_read_b128 v[168:171], v183 offset:128
	s_waitcnt lgkmcnt(2)
	v_mfma_f32_32x32x16_bf16 v[2:17], v[228:231], v[70:73], v[2:17]
	ds_read_b128 v[228:231], v183 offset:160
	s_waitcnt lgkmcnt(2)
	v_mfma_f32_32x32x16_bf16 v[2:17], v[242:245], v[66:69], v[2:17]
	ds_read_b128 v[242:245], v183 offset:192
	s_waitcnt lgkmcnt(2)
	v_mfma_f32_32x32x16_bf16 v[2:17], v[168:171], v[62:65], v[2:17]
	ds_read_b128 v[168:171], v183 offset:224
	s_waitcnt lgkmcnt(2)
	v_mfma_f32_32x32x16_bf16 v[2:17], v[228:231], v[58:61], v[2:17]
	s_waitcnt lgkmcnt(1)
	v_mfma_f32_32x32x16_bf16 v[2:17], v[242:245], v[54:57], v[2:17]
	s_waitcnt lgkmcnt(0)
	v_mfma_f32_32x32x16_bf16 v[2:17], v[168:171], v[50:53], v[2:17]
	s_nop 11
	v_mul_f32_e32 v2, v46, v2
	v_mul_f32_e32 v3, v47, v3
	v_cvt_pk_bf16_f32 v2, v2, v3
	v_mul_f32_e32 v3, v48, v4
	v_mul_f32_e32 v4, v49, v5
	v_cvt_pk_bf16_f32 v3, v3, v4
	v_lshl_add_u64 v[4:5], v[106:107], 0, v[0:1]
	global_store_dwordx2 v[4:5], v[2:3], off
	v_mul_f32_e32 v0, v42, v6
	v_mul_f32_e32 v2, v43, v7
	v_mul_f32_e32 v3, v45, v9
	v_cvt_pk_bf16_f32 v2, v0, v2
	v_mul_f32_e32 v0, v44, v8
	v_cvt_pk_bf16_f32 v3, v0, v3
	v_lshl_add_u64 v[4:5], v[106:107], 0, v[104:105]
	global_store_dwordx2 v[4:5], v[2:3], off
	v_mul_f32_e32 v0, v38, v10
	v_mul_f32_e32 v2, v39, v11
	v_mul_f32_e32 v3, v41, v13
	v_cvt_pk_bf16_f32 v2, v0, v2
	v_mul_f32_e32 v0, v40, v12
	v_cvt_pk_bf16_f32 v3, v0, v3
	v_lshl_add_u64 v[4:5], v[106:107], 0, v[108:109]
	global_store_dwordx2 v[4:5], v[2:3], off
	v_mul_f32_e32 v0, v34, v14
	v_mul_f32_e32 v2, v35, v15
	v_mul_f32_e32 v3, v37, v17
	v_lshl_add_u64 v[4:5], v[106:107], 0, v[102:103]
	v_cvt_pk_bf16_f32 v2, v0, v2
	v_mul_f32_e32 v0, v36, v16
	v_cvt_pk_bf16_f32 v3, v0, v3
	global_store_dwordx2 v[4:5], v[2:3], off
	ds_read_b128 v[2:5], v184
	ds_read_b128 v[34:37], v184 offset:32
	ds_read_b128 v[228:231], v184 offset:64
	ds_read_b128 v[242:245], v184 offset:96
	s_waitcnt lgkmcnt(3)
	v_mfma_f32_32x32x16_bf16 v[2:17], v[2:5], v[74:77], 0
	s_waitcnt lgkmcnt(2)
	v_mfma_f32_32x32x16_bf16 v[2:17], v[34:37], v[78:81], v[2:17]
	ds_read_b128 v[34:37], v184 offset:128
	s_waitcnt lgkmcnt(2)
	v_mfma_f32_32x32x16_bf16 v[2:17], v[228:231], v[70:73], v[2:17]
	ds_read_b128 v[228:231], v184 offset:160
	s_waitcnt lgkmcnt(2)
	v_mfma_f32_32x32x16_bf16 v[2:17], v[242:245], v[66:69], v[2:17]
	ds_read_b128 v[242:245], v184 offset:192
	s_waitcnt lgkmcnt(2)
	v_mfma_f32_32x32x16_bf16 v[2:17], v[34:37], v[62:65], v[2:17]
	ds_read_b128 v[34:37], v184 offset:224
	s_waitcnt lgkmcnt(2)
	v_mfma_f32_32x32x16_bf16 v[2:17], v[228:231], v[58:61], v[2:17]
	s_waitcnt lgkmcnt(1)
	v_mfma_f32_32x32x16_bf16 v[2:17], v[242:245], v[54:57], v[2:17]
	s_waitcnt lgkmcnt(0)
	v_mfma_f32_32x32x16_bf16 v[2:17], v[34:37], v[50:53], v[2:17]
	s_nop 11
	v_mul_f32_e32 v0, v30, v2
	v_mul_f32_e32 v2, v31, v3
	v_mul_f32_e32 v3, v33, v5
	v_cvt_pk_bf16_f32 v2, v0, v2
	v_mul_f32_e32 v0, v32, v4
	v_cvt_pk_bf16_f32 v3, v0, v3
	v_lshl_add_u64 v[4:5], v[106:107], 0, v[110:111]
	global_store_dwordx2 v[4:5], v[2:3], off
	v_mul_f32_e32 v0, v26, v6
	v_mul_f32_e32 v2, v27, v7
	v_mul_f32_e32 v3, v29, v9
	v_cvt_pk_bf16_f32 v2, v0, v2
	v_mul_f32_e32 v0, v28, v8
	v_cvt_pk_bf16_f32 v3, v0, v3
	v_lshl_add_u64 v[4:5], v[106:107], 0, v[112:113]
	global_store_dwordx2 v[4:5], v[2:3], off
	v_mul_f32_e32 v0, v22, v10
	v_mul_f32_e32 v2, v23, v11
	v_mul_f32_e32 v3, v25, v13
	v_cvt_pk_bf16_f32 v2, v0, v2
	v_mul_f32_e32 v0, v24, v12
	v_cvt_pk_bf16_f32 v3, v0, v3
	v_lshl_add_u64 v[4:5], v[106:107], 0, v[114:115]
	global_store_dwordx2 v[4:5], v[2:3], off
	v_mul_f32_e32 v0, v18, v14
	v_mul_f32_e32 v2, v19, v15
	v_mul_f32_e32 v3, v21, v17
	v_cvt_pk_bf16_f32 v2, v0, v2
	v_mul_f32_e32 v0, v20, v16
	v_cvt_pk_bf16_f32 v3, v0, v3

.Lpw_skip1:
.LBB0_220:
	s_or_b64 exec, exec, s[52:53]
	s_waitcnt vmcnt(26)
	v_cndmask_b32_e64 v14, 0, v14, s[8:9]
	v_cndmask_b32_e32 v10, 0, v10, vcc
	v_lshlrev_b32_e32 v65, 16, v14
	v_and_b32_e32 v66, 0xffff0000, v14
	v_add_u32_e32 v14, s95, v83
	s_waitcnt vmcnt(8)
	v_cndmask_b32_e64 v0, 0, v57, s[46:47]
	v_cndmask_b32_e64 v57, 0, v56, s[28:29]
	v_cndmask_b32_e64 v11, 0, v11, s[0:1]
	v_lshlrev_b32_e32 v56, 16, v10
	v_min_i32_e32 v14, 7, v14
	v_cndmask_b32_e64 v12, 0, v12, s[2:3]
	v_add_f32_e32 v58, 0, v56
	v_and_b32_e32 v59, 0xffff0000, v10
	v_lshlrev_b32_e32 v60, 16, v11
	v_add_u32_e32 v14, 1, v14
	v_add_f32_e32 v10, 0, v59
	v_add_f32_e32 v58, v58, v60
	v_and_b32_e32 v61, 0xffff0000, v11
	v_lshlrev_b32_e32 v62, 16, v12
	v_cvt_f32_i32_e32 v14, v14
	v_cndmask_b32_e64 v13, 0, v13, s[6:7]
	v_add_f32_e32 v10, v10, v61
	v_add_f32_e32 v11, v58, v62
	v_and_b32_e32 v58, 0xffff0000, v12
	v_add_f32_e32 v10, v10, v58
	v_lshlrev_b32_e32 v63, 16, v13
	v_and_b32_e32 v64, 0xffff0000, v13
	v_cndmask_b32_e64 v15, 0, v15, s[10:11]
	v_add_f32_e32 v11, v11, v63
	v_add_f32_e32 v10, v10, v64
	v_cndmask_b32_e64 v16, 0, v16, s[12:13]
	v_add_f32_e32 v11, v11, v65
	v_add_f32_e32 v10, v10, v66
	v_lshlrev_b32_e32 v67, 16, v15
	v_and_b32_e32 v68, 0xffff0000, v15
	v_rcp_iflag_f32_e32 v14, v14
	v_cndmask_b32_e64 v17, 0, v17, s[14:15]
	v_add_f32_e32 v11, v11, v67
	v_add_f32_e32 v10, v10, v68
	v_lshlrev_b32_e32 v69, 16, v16
	v_and_b32_e32 v70, 0xffff0000, v16
	v_add_f32_e32 v12, v11, v69
	v_add_f32_e32 v13, v10, v70
	v_lshlrev_b32_e32 v10, 16, v17
	v_and_b32_e32 v11, 0xffff0000, v17
	v_add_u32_e32 v16, s95, v127
	v_add_f32_e32 v12, v12, v10
	v_add_f32_e32 v13, v13, v11
	v_min_i32_e32 v16, 7, v16
	v_fma_f32 v15, v14, v12, -v10
	v_fma_f32 v14, v14, v13, -v11
	v_add_u32_e32 v16, 1, v16
	v_cndmask_b32_e64 v50, v50, 0, s[16:17]
	v_cvt_pk_bf16_f32 v14, v15, v14
	v_add_u32_e32 v116, 0, v145
	v_cvt_f32_i32_e32 v16, v16
	s_waitcnt lgkmcnt(0)
	s_barrier
	ds_write_b32 v116, v14 offset:34816
	v_sub_f32_e32 v14, v12, v56
	v_sub_f32_e32 v15, v13, v59
	v_lshlrev_b32_e32 v12, 16, v50
	v_and_b32_e32 v13, 0xffff0000, v50
	v_add_u32_e32 v50, s95, v128
	v_min_i32_e32 v50, 7, v50
	v_add_u32_e32 v50, 1, v50
	v_rcp_iflag_f32_e32 v16, v16
	v_cvt_f32_i32_e32 v50, v50
	v_add_f32_e32 v14, v14, v12
	v_add_f32_e32 v15, v15, v13
	v_fma_f32 v17, v16, v14, -v12
	v_fma_f32 v16, v16, v15, -v13
	v_rcp_iflag_f32_e32 v50, v50
	v_cndmask_b32_e64 v51, 0, v51, s[18:19]
	v_cvt_pk_bf16_f32 v16, v17, v16
	v_add_u32_e32 v117, 0, v146
	ds_write_b32 v117, v16 offset:34816
	v_sub_f32_e32 v16, v14, v60
	v_sub_f32_e32 v17, v15, v61
	v_lshlrev_b32_e32 v14, 16, v51
	v_and_b32_e32 v15, 0xffff0000, v51
	v_add_f32_e32 v16, v16, v14
	v_add_f32_e32 v17, v17, v15
	v_fma_f32 v51, v50, v16, -v14
	v_fma_f32 v50, v50, v17, -v15
	v_cndmask_b32_e64 v52, 0, v52, s[20:21]
	v_cvt_pk_bf16_f32 v50, v51, v50
	v_add_u32_e32 v168, 0, v147
	ds_write_b32 v168, v50 offset:34816
	v_sub_f32_e32 v50, v16, v62
	v_sub_f32_e32 v51, v17, v58
	v_lshlrev_b32_e32 v16, 16, v52
	v_and_b32_e32 v17, 0xffff0000, v52
	v_add_u32_e32 v52, s95, v129
	v_min_i32_e32 v52, 7, v52
	v_add_u32_e32 v52, 1, v52
	v_cvt_f32_i32_e32 v52, v52
	v_add_f32_e32 v50, v50, v16
	v_add_f32_e32 v51, v51, v17
	v_cndmask_b32_e64 v53, 0, v53, s[22:23]
	v_rcp_iflag_f32_e32 v52, v52
	v_add_u32_e32 v169, 0, v148
	v_cndmask_b32_e64 v54, 0, v54, s[24:25]
	v_add_u32_e32 v170, 0, v149
	v_fma_f32 v56, v52, v50, -v16
	v_fma_f32 v52, v52, v51, -v17
	v_cvt_pk_bf16_f32 v52, v56, v52
	v_sub_f32_e32 v56, v51, v64
	v_and_b32_e32 v51, 0xffff0000, v53
	ds_write_b32 v169, v52 offset:34816
	v_sub_f32_e32 v52, v50, v63
	v_lshlrev_b32_e32 v50, 16, v53
	v_add_f32_e32 v53, v56, v51
	v_add_u32_e32 v56, s95, v130
	v_min_i32_e32 v56, 7, v56
	v_add_u32_e32 v56, 1, v56
	v_cvt_f32_i32_e32 v56, v56
	v_add_f32_e32 v52, v52, v50
	v_cndmask_b32_e64 v55, 0, v55, s[26:27]
	v_add_u32_e32 v171, 0, v150
	v_rcp_iflag_f32_e32 v56, v56
	v_add_u32_e32 v172, 0, v151
	v_cndmask_b32_e64 v9, 0, v9, s[50:51]
	v_add_u32_e32 v173, 0, v152
	v_fma_f32 v58, v56, v52, -v50
	v_fma_f32 v56, v56, v53, -v51
	v_cvt_pk_bf16_f32 v56, v58, v56
	ds_write_b32 v170, v56 offset:34816
	v_sub_f32_e32 v56, v52, v65
	v_sub_f32_e32 v58, v53, v66
	v_lshlrev_b32_e32 v52, 16, v54
	v_and_b32_e32 v53, 0xffff0000, v54
	v_add_f32_e32 v54, v56, v52
	v_add_f32_e32 v56, v58, v53
	v_add_u32_e32 v58, s95, v131
	v_min_i32_e32 v58, 7, v58
	v_add_u32_e32 v58, 1, v58
	v_cvt_f32_i32_e32 v58, v58
	v_add_u32_e32 v174, 0, v153
	v_cndmask_b32_e64 v8, 0, v8, s[34:35]
	v_cndmask_b32_e64 v7, 0, v7, s[36:37]
	v_rcp_iflag_f32_e32 v58, v58
	v_add_u32_e32 v175, 0, v154
	v_cndmask_b32_e64 v6, 0, v6, s[38:39]
	v_add_u32_e32 v176, 0, v155
	v_fma_f32 v59, v58, v54, -v52
	v_fma_f32 v58, v58, v56, -v53
	v_cvt_pk_bf16_f32 v58, v59, v58
	v_add_u32_e32 v59, s95, v132
	v_min_i32_e32 v59, 7, v59
	v_add_u32_e32 v59, 1, v59
	v_cvt_f32_i32_e32 v59, v59
	ds_write_b32 v171, v58 offset:34816
	v_sub_f32_e32 v58, v54, v67
	v_sub_f32_e32 v56, v56, v68
	v_rcp_iflag_f32_e32 v59, v59
	v_lshlrev_b32_e32 v54, 16, v55
	v_and_b32_e32 v55, 0xffff0000, v55
	v_add_f32_e32 v58, v58, v54
	v_add_f32_e32 v56, v56, v55
	v_fma_f32 v60, v59, v58, -v54
	v_fma_f32 v59, v59, v56, -v55
	v_cvt_pk_bf16_f32 v59, v60, v59
	v_add_u32_e32 v60, s95, v133
	v_min_i32_e32 v60, 7, v60
	v_add_u32_e32 v60, 1, v60
	v_cvt_f32_i32_e32 v60, v60
	ds_write_b32 v172, v59 offset:34816
	v_sub_f32_e32 v58, v58, v69
	v_sub_f32_e32 v59, v56, v70
	v_rcp_iflag_f32_e32 v60, v60
	v_lshlrev_b32_e32 v56, 16, v57
	v_and_b32_e32 v57, 0xffff0000, v57
	v_add_f32_e32 v58, v58, v56
	v_add_f32_e32 v59, v59, v57
	v_fma_f32 v61, v60, v58, -v56
	v_fma_f32 v60, v60, v59, -v57
	v_sub_f32_e32 v11, v59, v11
	v_add_u32_e32 v59, s95, v134
	v_min_i32_e32 v59, 7, v59
	v_add_u32_e32 v59, 1, v59
	v_cvt_f32_i32_e32 v59, v59
	v_sub_f32_e32 v10, v58, v10
	v_lshlrev_b32_e32 v58, 16, v9
	v_and_b32_e32 v9, 0xffff0000, v9
	v_rcp_iflag_f32_e32 v59, v59
	v_add_f32_e32 v11, v11, v9
	v_add_f32_e32 v10, v10, v58
	v_cvt_pk_bf16_f32 v60, v61, v60
	v_fma_f32 v9, v59, v11, -v9
	v_fma_f32 v58, v59, v10, -v58
	v_cvt_pk_bf16_f32 v9, v58, v9
	ds_write_b32 v173, v60 offset:34816
	ds_write_b32 v174, v9 offset:34816
	v_sub_f32_e32 v9, v10, v12
	v_add_u32_e32 v12, s95, v135
	v_min_i32_e32 v12, 7, v12
	v_add_u32_e32 v12, 1, v12
	v_cvt_f32_i32_e32 v12, v12
	v_sub_f32_e32 v10, v11, v13
	v_lshlrev_b32_e32 v11, 16, v8
	v_and_b32_e32 v8, 0xffff0000, v8
	v_rcp_iflag_f32_e32 v12, v12
	v_add_f32_e32 v9, v9, v11
	v_add_f32_e32 v10, v10, v8
	v_cndmask_b32_e64 v5, 0, v5, s[40:41]
	v_fma_f32 v11, v12, v9, -v11
	v_fma_f32 v8, v12, v10, -v8
	v_cvt_pk_bf16_f32 v8, v11, v8
	v_add_u32_e32 v11, s95, v136
	v_min_i32_e32 v11, 7, v11
	v_add_u32_e32 v11, 1, v11
	v_cvt_f32_i32_e32 v11, v11
	ds_write_b32 v175, v8 offset:34816
	v_sub_f32_e32 v8, v9, v14
	v_sub_f32_e32 v9, v10, v15
	v_rcp_iflag_f32_e32 v11, v11
	v_lshlrev_b32_e32 v10, 16, v7
	v_and_b32_e32 v7, 0xffff0000, v7
	v_add_f32_e32 v8, v8, v10
	v_add_f32_e32 v9, v9, v7
	v_fma_f32 v10, v11, v8, -v10
	v_fma_f32 v7, v11, v9, -v7
	v_cvt_pk_bf16_f32 v7, v10, v7
	v_add_u32_e32 v10, s95, v137
	v_min_i32_e32 v10, 7, v10
	v_add_u32_e32 v10, 1, v10
	v_cvt_f32_i32_e32 v10, v10
	ds_write_b32 v176, v7 offset:34816
	v_sub_f32_e32 v7, v8, v16
	v_sub_f32_e32 v8, v9, v17
	v_rcp_iflag_f32_e32 v10, v10
	v_lshlrev_b32_e32 v9, 16, v6
	v_and_b32_e32 v6, 0xffff0000, v6
	v_add_f32_e32 v7, v7, v9
	v_add_f32_e32 v8, v8, v6
	v_fma_f32 v9, v10, v7, -v9
	v_fma_f32 v6, v10, v8, -v6
	v_cvt_pk_bf16_f32 v6, v9, v6
	v_add_u32_e32 v9, s95, v138
	v_min_i32_e32 v9, 7, v9
	v_add_u32_e32 v9, 1, v9
	v_cvt_f32_i32_e32 v9, v9
	v_add_u32_e32 v177, 0, v156
	ds_write_b32 v177, v6 offset:34816
	v_sub_f32_e32 v6, v7, v50
	v_rcp_iflag_f32_e32 v9, v9
	v_sub_f32_e32 v7, v8, v51
	v_lshlrev_b32_e32 v8, 16, v5
	v_and_b32_e32 v5, 0xffff0000, v5
	v_add_f32_e32 v6, v6, v8
	v_add_f32_e32 v7, v7, v5
	v_fma_f32 v8, v9, v6, -v8
	v_fma_f32 v5, v9, v7, -v5
	v_cvt_pk_bf16_f32 v5, v8, v5
	v_add_u32_e32 v8, s95, v139
	v_min_i32_e32 v8, 7, v8
	v_add_u32_e32 v8, 1, v8
	v_cvt_f32_i32_e32 v8, v8
	v_cndmask_b32_e64 v4, 0, v4, s[42:43]
	v_add_u32_e32 v178, 0, v157
	ds_write_b32 v178, v5 offset:34816
	v_rcp_iflag_f32_e32 v8, v8
	v_sub_f32_e32 v5, v6, v52
	v_sub_f32_e32 v6, v7, v53
	v_lshlrev_b32_e32 v7, 16, v4
	v_and_b32_e32 v4, 0xffff0000, v4
	v_add_f32_e32 v5, v5, v7
	v_add_f32_e32 v6, v6, v4
	v_fma_f32 v7, v8, v5, -v7
	v_fma_f32 v4, v8, v6, -v4
	v_cvt_pk_bf16_f32 v4, v7, v4
	v_add_u32_e32 v7, s95, v140
	v_min_i32_e32 v7, 7, v7
	v_add_u32_e32 v7, 1, v7
	v_cvt_f32_i32_e32 v7, v7
	v_cndmask_b32_e64 v3, 0, v3, s[44:45]
	v_add_u32_e32 v179, 0, v158
	ds_write_b32 v179, v4 offset:34816
	v_rcp_iflag_f32_e32 v7, v7
	v_sub_f32_e32 v4, v5, v54
	v_sub_f32_e32 v5, v6, v55
	v_lshlrev_b32_e32 v6, 16, v3
	v_and_b32_e32 v3, 0xffff0000, v3
	v_add_f32_e32 v4, v4, v6
	v_add_f32_e32 v5, v5, v3
	v_fma_f32 v6, v7, v4, -v6
	v_fma_f32 v3, v7, v5, -v3
	v_cvt_pk_bf16_f32 v3, v6, v3
	v_add_u32_e32 v6, s95, v141
	v_min_i32_e32 v6, 7, v6
	v_add_u32_e32 v6, 1, v6
	v_cvt_f32_i32_e32 v6, v6
	v_add_u32_e32 v180, 0, v159
	ds_write_b32 v180, v3 offset:34816
	v_sub_f32_e32 v3, v4, v56
	v_rcp_iflag_f32_e32 v6, v6
	v_sub_f32_e32 v4, v5, v57
	v_lshlrev_b32_e32 v5, 16, v0
	v_and_b32_e32 v0, 0xffff0000, v0
	s_or_b32 s0, s94, 0x80
	v_add_f32_e32 v3, v3, v5
	v_add_f32_e32 v4, v4, v0
	s_xor_b32 s1, s95, 0xffffff7f
	s_mul_i32 s2, s0, 0x1e00
	v_fma_f32 v3, v6, v3, -v5
	v_fma_f32 v0, v6, v4, -v0
	s_mul_hi_i32 s3, s0, 0x1e00
	s_add_u32 s2, s91, s2
	v_cvt_pk_bf16_f32 v0, v3, v0
	s_addc_u32 s3, s92, s3
	v_mov_b32_e32 v3, v1
	v_add_u32_e32 v181, 0, v160
	v_cmp_lt_i32_e32 vcc, s1, v141
	v_lshl_add_u64 v[2:3], s[2:3], 0, v[2:3]
	s_mov_b64 s[2:3], 0x1620
	ds_write_b32 v181, v0 offset:34816
	v_lshl_add_u64 v[2:3], v[2:3], 0, s[2:3]
	v_cndmask_b32_e32 v0, 0, v141, vcc
	s_movk_i32 s6, 0x1e00
	v_mad_i64_i32 v[4:5], s[2:3], v0, s6, v[2:3]
	global_load_dword v0, v[4:5], off
	v_add_u32_e32 v185, v144, v143
	v_add_u32_e32 v183, v144, v161
	v_lshlrev_b32_e32 v104, 1, v90
	v_mov_b32_e32 v105, v1
	v_mov_b32_e32 v103, v1
	v_add_u32_e32 v184, v144, v163
	v_lshlrev_b32_e32 v114, 1, v98
	v_mov_b32_e32 v115, v1
	s_waitcnt vmcnt(0)
	v_cndmask_b32_e32 v182, 0, v0, vcc
	v_cmp_lt_i32_e32 vcc, s1, v120
	v_mov_b32_e32 v211, 0
	s_nop 0
	v_cndmask_b32_e32 v0, 0, v120, vcc
	v_mad_i64_i32 v[4:5], s[2:3], v0, s6, v[2:3]
	s_and_saveexec_b64 s[98:99], vcc
	global_load_dword v211, v[4:5], off
	s_mov_b64 exec, s[98:99]
	v_cmp_lt_i32_e32 vcc, s1, v121
	v_mov_b32_e32 v212, 0
	s_nop 0
	v_cndmask_b32_e32 v0, 0, v121, vcc
	v_mad_i64_i32 v[4:5], s[2:3], v0, s6, v[2:3]
	s_and_saveexec_b64 s[98:99], vcc
	global_load_dword v212, v[4:5], off
	s_mov_b64 exec, s[98:99]
	v_cmp_lt_i32_e32 vcc, s1, v122
	v_mov_b32_e32 v213, 0
	s_nop 0
	v_cndmask_b32_e32 v0, 0, v122, vcc
	v_mad_i64_i32 v[4:5], s[2:3], v0, s6, v[2:3]
	s_and_saveexec_b64 s[98:99], vcc
	global_load_dword v213, v[4:5], off
	s_mov_b64 exec, s[98:99]
	v_cmp_lt_i32_e32 vcc, s1, v123
	v_mov_b32_e32 v214, 0
	s_nop 0
	v_cndmask_b32_e32 v0, 0, v123, vcc
	v_mad_i64_i32 v[4:5], s[2:3], v0, s6, v[2:3]
	s_and_saveexec_b64 s[98:99], vcc
	global_load_dword v214, v[4:5], off
	s_mov_b64 exec, s[98:99]
	v_cmp_lt_i32_e32 vcc, s1, v124
	v_mov_b32_e32 v215, 0
	s_nop 0
	v_cndmask_b32_e32 v0, 0, v124, vcc
	v_mad_i64_i32 v[4:5], s[2:3], v0, s6, v[2:3]
	s_and_saveexec_b64 s[98:99], vcc
	global_load_dword v215, v[4:5], off
	s_mov_b64 exec, s[98:99]
	v_cmp_lt_i32_e32 vcc, s1, v125
	v_mov_b32_e32 v216, 0
	s_nop 0
	v_cndmask_b32_e32 v0, 0, v125, vcc
	v_mad_i64_i32 v[4:5], s[2:3], v0, s6, v[2:3]
	s_and_saveexec_b64 s[98:99], vcc
	global_load_dword v216, v[4:5], off
	s_mov_b64 exec, s[98:99]
	v_cmp_lt_i32_e32 vcc, s1, v126
	v_mov_b32_e32 v218, 0
	s_nop 0
	v_cndmask_b32_e32 v0, 0, v126, vcc
	v_mad_i64_i32 v[4:5], s[2:3], v0, s6, v[2:3]
	s_and_saveexec_b64 s[98:99], vcc
	global_load_dword v218, v[4:5], off
	s_mov_b64 exec, s[98:99]
	v_cmp_lt_i32_e32 vcc, s1, v83
	v_mov_b32_e32 v217, 0
	s_nop 0
	v_cndmask_b32_e32 v0, 0, v83, vcc
	v_mad_i64_i32 v[4:5], s[2:3], v0, s6, v[2:3]
	s_and_saveexec_b64 s[98:99], vcc
	global_load_dword v217, v[4:5], off
	s_mov_b64 exec, s[98:99]
	v_cmp_gt_i32_e32 vcc, s1, v83
	s_nop 1
	v_cndmask_b32_e64 v0, v127, 0, vcc
	v_mad_i64_i32 v[4:5], s[2:3], v0, s6, v[2:3]
	global_load_dword v0, v[4:5], off
	s_waitcnt vmcnt(0)
	v_cndmask_b32_e64 v191, v0, 0, vcc
	v_cmp_lt_i32_e32 vcc, s1, v128
	v_mov_b32_e32 v210, 0
	s_nop 0
	v_cndmask_b32_e32 v0, 0, v128, vcc
	v_mad_i64_i32 v[4:5], s[2:3], v0, s6, v[2:3]
	s_and_saveexec_b64 s[98:99], vcc
	global_load_dword v210, v[4:5], off
	s_mov_b64 exec, s[98:99]
	v_cmp_lt_i32_e32 vcc, s1, v129
	v_mov_b32_e32 v209, 0
	s_nop 0
	v_cndmask_b32_e32 v0, 0, v129, vcc
	v_mad_i64_i32 v[4:5], s[2:3], v0, s6, v[2:3]
	s_and_saveexec_b64 s[98:99], vcc
	global_load_dword v209, v[4:5], off
	s_mov_b64 exec, s[98:99]
	v_cmp_lt_i32_e32 vcc, s1, v130
	v_mov_b32_e32 v208, 0
	s_nop 0
	v_cndmask_b32_e32 v0, 0, v130, vcc
	v_mad_i64_i32 v[4:5], s[2:3], v0, s6, v[2:3]
	s_and_saveexec_b64 s[98:99], vcc
	global_load_dword v208, v[4:5], off
	s_mov_b64 exec, s[98:99]
	v_cmp_lt_i32_e32 vcc, s1, v131
	v_mov_b32_e32 v207, 0
	s_nop 0
	v_cndmask_b32_e32 v0, 0, v131, vcc
	v_mad_i64_i32 v[4:5], s[2:3], v0, s6, v[2:3]
	s_and_saveexec_b64 s[98:99], vcc
	global_load_dword v207, v[4:5], off
	s_mov_b64 exec, s[98:99]
	v_cmp_lt_i32_e32 vcc, s1, v132
	v_mov_b32_e32 v206, 0
	s_nop 0
	v_cndmask_b32_e32 v0, 0, v132, vcc
	v_mad_i64_i32 v[4:5], s[2:3], v0, s6, v[2:3]
	s_and_saveexec_b64 s[98:99], vcc
	global_load_dword v206, v[4:5], off
	s_mov_b64 exec, s[98:99]
	v_cmp_lt_i32_e32 vcc, s1, v133
	v_mov_b32_e32 v205, 0
	s_nop 0
	v_cndmask_b32_e32 v0, 0, v133, vcc
	v_mad_i64_i32 v[4:5], s[2:3], v0, s6, v[2:3]
	s_and_saveexec_b64 s[98:99], vcc
	global_load_dword v205, v[4:5], off
	s_mov_b64 exec, s[98:99]
	v_cmp_lt_i32_e32 vcc, s1, v134
	v_mov_b32_e32 v204, 0
	s_nop 0
	v_cndmask_b32_e32 v0, 0, v134, vcc
	v_mad_i64_i32 v[4:5], s[2:3], v0, s6, v[2:3]
	s_and_saveexec_b64 s[98:99], vcc
	global_load_dword v204, v[4:5], off
	s_mov_b64 exec, s[98:99]
	v_cmp_lt_i32_e32 vcc, s1, v135
	v_mov_b32_e32 v192, 0
	s_nop 0
	v_cndmask_b32_e32 v0, 0, v135, vcc
	v_mad_i64_i32 v[4:5], s[2:3], v0, s6, v[2:3]
	s_and_saveexec_b64 s[98:99], vcc
	global_load_dword v192, v[4:5], off
	s_mov_b64 exec, s[98:99]
	v_cmp_lt_i32_e32 vcc, s1, v136
	v_mov_b32_e32 v190, 0
	s_nop 0
	v_cndmask_b32_e32 v0, 0, v136, vcc
	v_mad_i64_i32 v[4:5], s[2:3], v0, s6, v[2:3]
	s_and_saveexec_b64 s[98:99], vcc
	global_load_dword v190, v[4:5], off
	s_mov_b64 exec, s[98:99]
	v_cmp_lt_i32_e32 vcc, s1, v137
	v_mov_b32_e32 v189, 0
	s_nop 0
	v_cndmask_b32_e32 v0, 0, v137, vcc
	v_mad_i64_i32 v[4:5], s[2:3], v0, s6, v[2:3]
	s_and_saveexec_b64 s[98:99], vcc
	global_load_dword v189, v[4:5], off
	s_mov_b64 exec, s[98:99]
	v_cmp_lt_i32_e32 vcc, s1, v138
	v_mov_b32_e32 v188, 0
	s_nop 0
	v_cndmask_b32_e32 v0, 0, v138, vcc
	v_mad_i64_i32 v[4:5], s[2:3], v0, s6, v[2:3]
	s_and_saveexec_b64 s[98:99], vcc
	global_load_dword v188, v[4:5], off
	s_mov_b64 exec, s[98:99]
	v_cmp_lt_i32_e32 vcc, s1, v139
	v_mov_b32_e32 v187, 0
	s_nop 0
	v_cndmask_b32_e32 v0, 0, v139, vcc
	v_mad_i64_i32 v[4:5], s[2:3], v0, s6, v[2:3]
	s_and_saveexec_b64 s[98:99], vcc
	global_load_dword v187, v[4:5], off
	s_mov_b64 exec, s[98:99]
	v_cmp_lt_i32_e32 vcc, s1, v140
	s_and_b32 s1, s0, 0xf80
	s_nop 0
	v_cndmask_b32_e32 v0, 0, v140, vcc
	v_mad_i64_i32 v[2:3], s[2:3], v0, s6, v[2:3]
	global_load_dword v0, v[2:3], off
	v_add_u32_e32 v2, s94, v142
	v_ashrrev_i32_e32 v3, 31, v2
	v_lshlrev_b64 v[2:3], 12, v[2:3]
	s_waitcnt lgkmcnt(0)
	s_barrier
	v_lshl_add_u64 v[2:3], s[70:71], 0, v[2:3]
	s_mov_b64 s[2:3], 0x26000a00
	ds_read_b128 v[74:77], v185 offset:34816
	ds_read_b128 v[78:81], v185 offset:34848
	ds_read_b128 v[70:73], v185 offset:34880
	ds_read_b128 v[66:69], v185 offset:34912
	ds_read_b128 v[62:65], v185 offset:34944
	ds_read_b128 v[58:61], v185 offset:34976
	ds_read_b128 v[54:57], v185 offset:35008
	ds_read_b128 v[50:53], v185 offset:35040
	v_lshl_add_u64 v[106:107], v[2:3], 0, s[2:3]
	ds_read_b128 v[2:5], v183
	ds_read_b128 v[108:111], v183 offset:32
	ds_read_b128 v[228:231], v183 offset:64
	ds_read_b128 v[242:245], v183 offset:96
	s_waitcnt lgkmcnt(3)
	v_mfma_f32_32x32x16_bf16 v[2:17], v[2:5], v[74:77], 0
	s_waitcnt vmcnt(0)
	v_cndmask_b32_e32 v186, 0, v0, vcc
	s_waitcnt lgkmcnt(2)
	v_mfma_f32_32x32x16_bf16 v[2:17], v[108:111], v[78:81], v[2:17]
	ds_read_b128 v[108:111], v183 offset:128
	s_waitcnt lgkmcnt(2)
	v_mfma_f32_32x32x16_bf16 v[2:17], v[228:231], v[70:73], v[2:17]
	ds_read_b128 v[228:231], v183 offset:160
	s_waitcnt lgkmcnt(2)
	v_mfma_f32_32x32x16_bf16 v[2:17], v[242:245], v[66:69], v[2:17]
	ds_read_b128 v[242:245], v183 offset:192
	s_waitcnt lgkmcnt(2)
	v_mfma_f32_32x32x16_bf16 v[2:17], v[108:111], v[62:65], v[2:17]
	ds_read_b128 v[108:111], v183 offset:224
	s_waitcnt lgkmcnt(2)
	v_mfma_f32_32x32x16_bf16 v[2:17], v[228:231], v[58:61], v[2:17]
	s_waitcnt lgkmcnt(1)
	v_mfma_f32_32x32x16_bf16 v[2:17], v[242:245], v[54:57], v[2:17]
	s_waitcnt lgkmcnt(0)
	v_mfma_f32_32x32x16_bf16 v[2:17], v[108:111], v[50:53], v[2:17]
	v_lshlrev_b32_e32 v108, 1, v92
	v_mov_b32_e32 v109, v1
	s_nop 9
	v_mul_f32_e32 v0, v46, v2
	v_mul_f32_e32 v2, v47, v3
	v_cvt_pk_bf16_f32 v2, v0, v2
	v_mul_f32_e32 v0, v48, v4
	v_mul_f32_e32 v3, v49, v5
	v_cvt_pk_bf16_f32 v3, v0, v3
	v_lshlrev_b32_e32 v0, 1, v88
	v_lshl_add_u64 v[4:5], v[106:107], 0, v[0:1]
	global_store_dwordx2 v[4:5], v[2:3], off
	v_mul_f32_e32 v2, v42, v6
	v_mul_f32_e32 v3, v43, v7
	v_cvt_pk_bf16_f32 v2, v2, v3
	v_mul_f32_e32 v3, v44, v8
	v_mul_f32_e32 v4, v45, v9
	v_cvt_pk_bf16_f32 v3, v3, v4
	v_lshl_add_u64 v[4:5], v[106:107], 0, v[104:105]
	global_store_dwordx2 v[4:5], v[2:3], off
	v_mul_f32_e32 v2, v38, v10
	v_mul_f32_e32 v3, v39, v11
	v_cvt_pk_bf16_f32 v2, v2, v3
	v_mul_f32_e32 v3, v40, v12
	v_mul_f32_e32 v4, v41, v13
	v_cvt_pk_bf16_f32 v3, v3, v4
	v_lshl_add_u64 v[4:5], v[106:107], 0, v[108:109]
	global_store_dwordx2 v[4:5], v[2:3], off
	v_mul_f32_e32 v2, v34, v14
	v_mul_f32_e32 v3, v35, v15
	v_cvt_pk_bf16_f32 v2, v2, v3
	v_mul_f32_e32 v3, v36, v16
	v_mul_f32_e32 v4, v37, v17
	v_cvt_pk_bf16_f32 v3, v3, v4
	v_lshl_add_u64 v[4:5], v[106:107], 0, v[102:103]
	global_store_dwordx2 v[4:5], v[2:3], off
	ds_read_b128 v[228:231], v184
	ds_read_b128 v[242:245], v184 offset:32
	ds_read_b128 v[246:249], v184 offset:64
	s_waitcnt lgkmcnt(2)
	v_mfma_f32_32x32x16_bf16 v[2:17], v[228:231], v[74:77], 0
	ds_read_b128 v[228:231], v184 offset:96
	s_waitcnt lgkmcnt(2)
	v_mfma_f32_32x32x16_bf16 v[2:17], v[242:245], v[78:81], v[2:17]
	ds_read_b128 v[242:245], v184 offset:128
	v_lshlrev_b32_e32 v110, 1, v94
	v_mov_b32_e32 v111, v1
	v_lshlrev_b32_e32 v112, 1, v96
	v_mov_b32_e32 v113, v1
	s_waitcnt lgkmcnt(2)
	v_mfma_f32_32x32x16_bf16 v[2:17], v[246:249], v[70:73], v[2:17]
	ds_read_b128 v[246:249], v184 offset:160
	s_waitcnt lgkmcnt(2)
	v_mfma_f32_32x32x16_bf16 v[2:17], v[228:231], v[66:69], v[2:17]
	ds_read_b128 v[228:231], v184 offset:192
	s_waitcnt lgkmcnt(2)
	v_mfma_f32_32x32x16_bf16 v[2:17], v[242:245], v[62:65], v[2:17]
	ds_read_b128 v[242:245], v184 offset:224
	s_waitcnt lgkmcnt(2)
	v_mfma_f32_32x32x16_bf16 v[2:17], v[246:249], v[58:61], v[2:17]
	s_waitcnt lgkmcnt(1)
	v_mfma_f32_32x32x16_bf16 v[2:17], v[228:231], v[54:57], v[2:17]
	s_waitcnt lgkmcnt(0)
	v_mfma_f32_32x32x16_bf16 v[2:17], v[242:245], v[50:53], v[2:17]
	v_add_u32_e32 v52, s1, v83
	v_min_i32_e32 v52, 7, v52
	v_add_u32_e32 v52, 1, v52
	v_cvt_f32_i32_e32 v52, v52
	v_lshlrev_b32_e32 v50, 16, v217
	v_and_b32_e32 v51, 0xffff0000, v217
	s_nop 5
	v_mul_f32_e32 v2, v30, v2
	v_mul_f32_e32 v3, v31, v3
	v_cvt_pk_bf16_f32 v2, v2, v3
	v_mul_f32_e32 v3, v32, v4
	v_mul_f32_e32 v4, v33, v5
	v_cvt_pk_bf16_f32 v3, v3, v4
	v_lshl_add_u64 v[4:5], v[106:107], 0, v[110:111]
	global_store_dwordx2 v[4:5], v[2:3], off
	v_mul_f32_e32 v2, v26, v6
	v_mul_f32_e32 v3, v27, v7
	v_cvt_pk_bf16_f32 v2, v2, v3
	v_mul_f32_e32 v3, v28, v8
	v_mul_f32_e32 v4, v29, v9
	v_cvt_pk_bf16_f32 v3, v3, v4
	v_lshl_add_u64 v[4:5], v[106:107], 0, v[112:113]
	global_store_dwordx2 v[4:5], v[2:3], off
	v_mul_f32_e32 v2, v22, v10
	v_mul_f32_e32 v3, v23, v11
	v_cvt_pk_bf16_f32 v2, v2, v3
	v_mul_f32_e32 v3, v24, v12
	v_mul_f32_e32 v4, v25, v13
	v_cvt_pk_bf16_f32 v3, v3, v4
	v_lshl_add_u64 v[4:5], v[106:107], 0, v[114:115]
	global_store_dwordx2 v[4:5], v[2:3], off
	v_mul_f32_e32 v2, v18, v14
	v_mul_f32_e32 v3, v19, v15
	v_cvt_pk_bf16_f32 v2, v2, v3
	v_mul_f32_e32 v3, v20, v16
	v_mul_f32_e32 v4, v21, v17
	v_cvt_pk_bf16_f32 v3, v3, v4
	v_lshlrev_b32_e32 v4, 1, v100
	v_mov_b32_e32 v5, v1
	v_lshl_add_u64 v[4:5], v[106:107], 0, v[4:5]
	global_store_dwordx2 v[4:5], v[2:3], off
	v_lshlrev_b32_e32 v2, 16, v211
	v_and_b32_e32 v4, 0xffff0000, v211
	v_add_f32_e32 v3, 0, v2
	v_add_f32_e32 v5, 0, v4
	v_lshlrev_b32_e32 v6, 16, v212
	v_and_b32_e32 v7, 0xffff0000, v212
	v_add_f32_e32 v3, v3, v6
	v_add_f32_e32 v5, v5, v7
	v_lshlrev_b32_e32 v8, 16, v213
	v_and_b32_e32 v9, 0xffff0000, v213
	v_add_f32_e32 v3, v3, v8
	v_add_f32_e32 v5, v5, v9
	v_lshlrev_b32_e32 v10, 16, v214
	v_and_b32_e32 v11, 0xffff0000, v214
	v_add_f32_e32 v3, v3, v10
	v_add_f32_e32 v5, v5, v11
	v_lshlrev_b32_e32 v12, 16, v215
	v_and_b32_e32 v13, 0xffff0000, v215
	v_add_f32_e32 v3, v3, v12
	v_add_f32_e32 v5, v5, v13
	v_lshlrev_b32_e32 v14, 16, v216
	v_and_b32_e32 v15, 0xffff0000, v216
	v_rcp_iflag_f32_e32 v52, v52
	v_add_f32_e32 v3, v3, v14
	v_add_f32_e32 v5, v5, v15
	v_lshlrev_b32_e32 v16, 16, v218
	v_and_b32_e32 v17, 0xffff0000, v218
	v_add_f32_e32 v3, v3, v16
	v_add_f32_e32 v5, v5, v17
	v_add_f32_e32 v3, v3, v50
	v_add_f32_e32 v5, v5, v51
	v_fma_f32 v53, v52, v3, -v50
	v_fma_f32 v52, v52, v5, -v51
	v_cvt_pk_bf16_f32 v52, v53, v52
	s_waitcnt lgkmcnt(0)
	s_barrier
	ds_write_b32 v116, v52 offset:34816
	v_add_u32_e32 v52, s1, v127
	v_min_i32_e32 v52, 7, v52
	v_add_u32_e32 v52, 1, v52
	v_cvt_f32_i32_e32 v52, v52
	v_sub_f32_e32 v2, v3, v2
	v_sub_f32_e32 v3, v5, v4
	v_lshlrev_b32_e32 v4, 16, v191
	v_rcp_iflag_f32_e32 v52, v52
	v_and_b32_e32 v5, 0xffff0000, v191
	v_add_f32_e32 v2, v2, v4
	v_add_f32_e32 v3, v3, v5
	v_fma_f32 v53, v52, v2, -v4
	v_fma_f32 v52, v52, v3, -v5
	v_cvt_pk_bf16_f32 v52, v53, v52
	ds_write_b32 v117, v52 offset:34816
	v_add_u32_e32 v52, s1, v128
	v_min_i32_e32 v52, 7, v52
	v_add_u32_e32 v52, 1, v52
	v_cvt_f32_i32_e32 v52, v52
	v_sub_f32_e32 v2, v2, v6
	v_sub_f32_e32 v3, v3, v7
	v_lshlrev_b32_e32 v6, 16, v210
	v_rcp_iflag_f32_e32 v52, v52
	v_and_b32_e32 v7, 0xffff0000, v210
	v_add_f32_e32 v2, v2, v6
	v_add_f32_e32 v3, v3, v7
	v_fma_f32 v53, v52, v2, -v6
	v_fma_f32 v52, v52, v3, -v7
	v_cvt_pk_bf16_f32 v52, v53, v52
	ds_write_b32 v168, v52 offset:34816
	v_add_u32_e32 v52, s1, v129
	v_min_i32_e32 v52, 7, v52
	v_add_u32_e32 v52, 1, v52
	v_cvt_f32_i32_e32 v52, v52
	v_sub_f32_e32 v2, v2, v8
	v_sub_f32_e32 v3, v3, v9
	v_lshlrev_b32_e32 v8, 16, v209
	v_rcp_iflag_f32_e32 v52, v52
	v_and_b32_e32 v9, 0xffff0000, v209
	v_add_f32_e32 v2, v2, v8
	v_add_f32_e32 v3, v3, v9
	v_fma_f32 v53, v52, v2, -v8
	v_fma_f32 v52, v52, v3, -v9
	v_cvt_pk_bf16_f32 v52, v53, v52
	ds_write_b32 v169, v52 offset:34816
	v_add_u32_e32 v52, s1, v130
	v_min_i32_e32 v52, 7, v52
	v_add_u32_e32 v52, 1, v52
	v_cvt_f32_i32_e32 v52, v52
	v_sub_f32_e32 v2, v2, v10
	v_sub_f32_e32 v3, v3, v11
	v_lshlrev_b32_e32 v10, 16, v208
	v_rcp_iflag_f32_e32 v52, v52
	v_and_b32_e32 v11, 0xffff0000, v208
	v_add_f32_e32 v2, v2, v10
	v_add_f32_e32 v3, v3, v11
	v_fma_f32 v53, v52, v2, -v10
	v_fma_f32 v52, v52, v3, -v11
	v_cvt_pk_bf16_f32 v52, v53, v52
	ds_write_b32 v170, v52 offset:34816
	v_add_u32_e32 v52, s1, v131
	v_min_i32_e32 v52, 7, v52
	v_add_u32_e32 v52, 1, v52
	v_cvt_f32_i32_e32 v52, v52
	v_sub_f32_e32 v2, v2, v12
	v_sub_f32_e32 v3, v3, v13
	v_lshlrev_b32_e32 v12, 16, v207
	v_rcp_iflag_f32_e32 v52, v52
	v_and_b32_e32 v13, 0xffff0000, v207
	v_add_f32_e32 v2, v2, v12
	v_add_f32_e32 v3, v3, v13
	v_fma_f32 v53, v52, v2, -v12
	v_fma_f32 v52, v52, v3, -v13
	v_cvt_pk_bf16_f32 v52, v53, v52
	ds_write_b32 v171, v52 offset:34816
	v_add_u32_e32 v52, s1, v132
	v_min_i32_e32 v52, 7, v52
	v_add_u32_e32 v52, 1, v52
	v_cvt_f32_i32_e32 v52, v52
	v_sub_f32_e32 v2, v2, v14
	v_sub_f32_e32 v3, v3, v15
	v_lshlrev_b32_e32 v14, 16, v206
	v_rcp_iflag_f32_e32 v52, v52
	v_and_b32_e32 v15, 0xffff0000, v206
	v_add_f32_e32 v2, v2, v14
	v_add_f32_e32 v3, v3, v15
	v_fma_f32 v53, v52, v2, -v14
	v_fma_f32 v52, v52, v3, -v15
	v_cvt_pk_bf16_f32 v52, v53, v52
	ds_write_b32 v172, v52 offset:34816
	v_add_u32_e32 v52, s1, v133
	v_min_i32_e32 v52, 7, v52
	v_add_u32_e32 v52, 1, v52
	v_cvt_f32_i32_e32 v52, v52
	v_sub_f32_e32 v2, v2, v16
	v_sub_f32_e32 v3, v3, v17
	v_lshlrev_b32_e32 v16, 16, v205
	v_rcp_iflag_f32_e32 v52, v52
	v_and_b32_e32 v17, 0xffff0000, v205
	v_add_f32_e32 v2, v2, v16
	v_add_f32_e32 v3, v3, v17
	v_fma_f32 v53, v52, v2, -v16
	v_fma_f32 v52, v52, v3, -v17
	v_cvt_pk_bf16_f32 v52, v53, v52
	ds_write_b32 v173, v52 offset:34816
	v_add_u32_e32 v52, s1, v134
	v_min_i32_e32 v52, 7, v52
	v_add_u32_e32 v52, 1, v52
	v_cvt_f32_i32_e32 v52, v52
	v_sub_f32_e32 v2, v2, v50
	v_lshlrev_b32_e32 v50, 16, v204
	v_sub_f32_e32 v3, v3, v51
	v_rcp_iflag_f32_e32 v52, v52
	v_and_b32_e32 v51, 0xffff0000, v204
	v_add_f32_e32 v2, v2, v50
	v_add_f32_e32 v3, v3, v51
	v_fma_f32 v50, v52, v2, -v50
	v_fma_f32 v51, v52, v3, -v51
	v_cvt_pk_bf16_f32 v50, v50, v51
	ds_write_b32 v174, v50 offset:34816
	v_add_u32_e32 v50, s1, v135
	v_min_i32_e32 v50, 7, v50
	v_add_u32_e32 v50, 1, v50
	v_cvt_f32_i32_e32 v50, v50
	v_sub_f32_e32 v2, v2, v4
	v_lshlrev_b32_e32 v4, 16, v192
	v_add_f32_e32 v2, v2, v4
	v_rcp_iflag_f32_e32 v50, v50
	v_sub_f32_e32 v3, v3, v5
	v_and_b32_e32 v5, 0xffff0000, v192
	v_add_f32_e32 v3, v3, v5
	v_fma_f32 v4, v50, v2, -v4
	v_sub_f32_e32 v2, v2, v6
	v_add_u32_e32 v6, s1, v136
	v_min_i32_e32 v6, 7, v6
	v_add_u32_e32 v6, 1, v6
	v_cvt_f32_i32_e32 v6, v6
	v_fma_f32 v5, v50, v3, -v5
	v_cvt_pk_bf16_f32 v4, v4, v5
	ds_write_b32 v175, v4 offset:34816
	v_rcp_iflag_f32_e32 v6, v6
	v_sub_f32_e32 v3, v3, v7
	v_lshlrev_b32_e32 v4, 16, v190
	v_and_b32_e32 v5, 0xffff0000, v190
	v_add_f32_e32 v2, v2, v4
	v_add_f32_e32 v3, v3, v5
	v_fma_f32 v4, v6, v2, -v4
	v_fma_f32 v5, v6, v3, -v5
	v_add_u32_e32 v6, s1, v137
	v_min_i32_e32 v6, 7, v6
	v_add_u32_e32 v6, 1, v6
	v_cvt_f32_i32_e32 v6, v6
	v_cvt_pk_bf16_f32 v4, v4, v5
	ds_write_b32 v176, v4 offset:34816
	v_sub_f32_e32 v2, v2, v8
	v_rcp_iflag_f32_e32 v6, v6
	v_sub_f32_e32 v3, v3, v9
	v_lshlrev_b32_e32 v4, 16, v189
	v_and_b32_e32 v5, 0xffff0000, v189
	v_add_f32_e32 v2, v2, v4
	v_add_f32_e32 v3, v3, v5
	v_fma_f32 v4, v6, v2, -v4
	v_fma_f32 v5, v6, v3, -v5
	v_add_u32_e32 v6, s1, v138
	v_min_i32_e32 v6, 7, v6
	v_add_u32_e32 v6, 1, v6
	v_cvt_f32_i32_e32 v6, v6
	v_cvt_pk_bf16_f32 v4, v4, v5
	ds_write_b32 v177, v4 offset:34816
	v_sub_f32_e32 v2, v2, v10
	v_rcp_iflag_f32_e32 v6, v6
	v_sub_f32_e32 v3, v3, v11
	v_lshlrev_b32_e32 v4, 16, v188
	v_and_b32_e32 v5, 0xffff0000, v188
	v_add_f32_e32 v2, v2, v4
	v_add_f32_e32 v3, v3, v5
	v_fma_f32 v4, v6, v2, -v4
	v_fma_f32 v5, v6, v3, -v5
	v_add_u32_e32 v6, s1, v139
	v_min_i32_e32 v6, 7, v6
	v_add_u32_e32 v6, 1, v6
	v_cvt_f32_i32_e32 v6, v6
	v_cvt_pk_bf16_f32 v4, v4, v5
	ds_write_b32 v178, v4 offset:34816
	v_sub_f32_e32 v2, v2, v12
	v_rcp_iflag_f32_e32 v6, v6
	v_sub_f32_e32 v3, v3, v13
	v_lshlrev_b32_e32 v4, 16, v187
	v_and_b32_e32 v5, 0xffff0000, v187
	v_add_f32_e32 v2, v2, v4
	v_add_f32_e32 v3, v3, v5
	v_fma_f32 v4, v6, v2, -v4
	v_fma_f32 v5, v6, v3, -v5
	v_add_u32_e32 v6, s1, v140
	v_min_i32_e32 v6, 7, v6
	v_add_u32_e32 v6, 1, v6
	v_cvt_f32_i32_e32 v6, v6
	v_cvt_pk_bf16_f32 v4, v4, v5
	ds_write_b32 v179, v4 offset:34816
	v_sub_f32_e32 v2, v2, v14
	v_rcp_iflag_f32_e32 v6, v6
	v_sub_f32_e32 v3, v3, v15
	v_lshlrev_b32_e32 v4, 16, v186
	v_and_b32_e32 v5, 0xffff0000, v186
	v_add_f32_e32 v2, v2, v4
	v_add_f32_e32 v3, v3, v5
	v_fma_f32 v4, v6, v2, -v4
	v_fma_f32 v5, v6, v3, -v5
	v_add_u32_e32 v6, s1, v141
	v_min_i32_e32 v6, 7, v6
	v_add_u32_e32 v6, 1, v6
	v_cvt_f32_i32_e32 v6, v6
	v_cvt_pk_bf16_f32 v4, v4, v5
	ds_write_b32 v180, v4 offset:34816
	v_sub_f32_e32 v2, v2, v16
	v_rcp_iflag_f32_e32 v6, v6
	v_lshlrev_b32_e32 v4, 16, v182
	v_sub_f32_e32 v3, v3, v17
	v_and_b32_e32 v5, 0xffff0000, v182
	v_add_f32_e32 v2, v2, v4
	v_add_f32_e32 v3, v3, v5
	v_fma_f32 v2, v6, v2, -v4
	v_fma_f32 v3, v6, v3, -v5
	v_cvt_pk_bf16_f32 v2, v2, v3
	ds_write_b32 v181, v2 offset:34816
	v_add_u32_e32 v2, s0, v142
	v_ashrrev_i32_e32 v3, 31, v2
	v_lshlrev_b64 v[2:3], 12, v[2:3]
	s_waitcnt lgkmcnt(0)
	s_barrier
	v_lshl_add_u64 v[2:3], s[70:71], 0, v[2:3]
	ds_read_b128 v[74:77], v185 offset:34816
	ds_read_b128 v[78:81], v185 offset:34848
	ds_read_b128 v[70:73], v185 offset:34880
	ds_read_b128 v[66:69], v185 offset:34912
	ds_read_b128 v[62:65], v185 offset:34944
	ds_read_b128 v[58:61], v185 offset:34976
	ds_read_b128 v[54:57], v185 offset:35008
	ds_read_b128 v[50:53], v185 offset:35040
	v_lshl_add_u64 v[106:107], v[2:3], 0, s[2:3]
	ds_read_b128 v[2:5], v183
	ds_read_b128 v[168:171], v183 offset:32
	ds_read_b128 v[228:231], v183 offset:64
	ds_read_b128 v[242:245], v183 offset:96
	s_waitcnt lgkmcnt(3)
	v_mfma_f32_32x32x16_bf16 v[2:17], v[2:5], v[74:77], 0
	s_waitcnt lgkmcnt(2)
	v_mfma_f32_32x32x16_bf16 v[2:17], v[168:171], v[78:81], v[2:17]
	ds_read_b128 v[168:171], v183 offset:128
	s_waitcnt lgkmcnt(2)
	v_mfma_f32_32x32x16_bf16 v[2:17], v[228:231], v[70:73], v[2:17]
	ds_read_b128 v[228:231], v183 offset:160
	s_waitcnt lgkmcnt(2)
	v_mfma_f32_32x32x16_bf16 v[2:17], v[242:245], v[66:69], v[2:17]
	ds_read_b128 v[242:245], v183 offset:192
	s_waitcnt lgkmcnt(2)
	v_mfma_f32_32x32x16_bf16 v[2:17], v[168:171], v[62:65], v[2:17]
	ds_read_b128 v[168:171], v183 offset:224
	s_waitcnt lgkmcnt(2)
	v_mfma_f32_32x32x16_bf16 v[2:17], v[228:231], v[58:61], v[2:17]
	s_waitcnt lgkmcnt(1)
	v_mfma_f32_32x32x16_bf16 v[2:17], v[242:245], v[54:57], v[2:17]
	s_waitcnt lgkmcnt(0)
	v_mfma_f32_32x32x16_bf16 v[2:17], v[168:171], v[50:53], v[2:17]
	s_nop 11
	v_mul_f32_e32 v2, v46, v2
	v_mul_f32_e32 v3, v47, v3
	v_cvt_pk_bf16_f32 v2, v2, v3
	v_mul_f32_e32 v3, v48, v4
	v_mul_f32_e32 v4, v49, v5
	v_cvt_pk_bf16_f32 v3, v3, v4
	v_lshl_add_u64 v[4:5], v[106:107], 0, v[0:1]
	global_store_dwordx2 v[4:5], v[2:3], off
	v_mul_f32_e32 v0, v42, v6
	v_mul_f32_e32 v2, v43, v7
	v_mul_f32_e32 v3, v45, v9
	v_cvt_pk_bf16_f32 v2, v0, v2
	v_mul_f32_e32 v0, v44, v8
	v_cvt_pk_bf16_f32 v3, v0, v3
	v_lshl_add_u64 v[4:5], v[106:107], 0, v[104:105]
	global_store_dwordx2 v[4:5], v[2:3], off
	v_mul_f32_e32 v0, v38, v10
	v_mul_f32_e32 v2, v39, v11
	v_mul_f32_e32 v3, v41, v13
	v_cvt_pk_bf16_f32 v2, v0, v2
	v_mul_f32_e32 v0, v40, v12
	v_cvt_pk_bf16_f32 v3, v0, v3
	v_lshl_add_u64 v[4:5], v[106:107], 0, v[108:109]
	global_store_dwordx2 v[4:5], v[2:3], off
	v_mul_f32_e32 v0, v34, v14
	v_mul_f32_e32 v2, v35, v15
	v_mul_f32_e32 v3, v37, v17
	v_lshl_add_u64 v[4:5], v[106:107], 0, v[102:103]
	v_cvt_pk_bf16_f32 v2, v0, v2
	v_mul_f32_e32 v0, v36, v16
	v_cvt_pk_bf16_f32 v3, v0, v3
	global_store_dwordx2 v[4:5], v[2:3], off
	ds_read_b128 v[2:5], v184
	ds_read_b128 v[34:37], v184 offset:32
	ds_read_b128 v[228:231], v184 offset:64
	ds_read_b128 v[242:245], v184 offset:96
	s_waitcnt lgkmcnt(3)
	v_mfma_f32_32x32x16_bf16 v[2:17], v[2:5], v[74:77], 0
	s_waitcnt lgkmcnt(2)
	v_mfma_f32_32x32x16_bf16 v[2:17], v[34:37], v[78:81], v[2:17]
	ds_read_b128 v[34:37], v184 offset:128
	s_waitcnt lgkmcnt(2)
	v_mfma_f32_32x32x16_bf16 v[2:17], v[228:231], v[70:73], v[2:17]
	ds_read_b128 v[228:231], v184 offset:160
	s_waitcnt lgkmcnt(2)
	v_mfma_f32_32x32x16_bf16 v[2:17], v[242:245], v[66:69], v[2:17]
	ds_read_b128 v[242:245], v184 offset:192
	s_waitcnt lgkmcnt(2)
	v_mfma_f32_32x32x16_bf16 v[2:17], v[34:37], v[62:65], v[2:17]
	ds_read_b128 v[34:37], v184 offset:224
	s_waitcnt lgkmcnt(2)
	v_mfma_f32_32x32x16_bf16 v[2:17], v[228:231], v[58:61], v[2:17]
	s_waitcnt lgkmcnt(1)
	v_mfma_f32_32x32x16_bf16 v[2:17], v[242:245], v[54:57], v[2:17]
	s_waitcnt lgkmcnt(0)
	v_mfma_f32_32x32x16_bf16 v[2:17], v[34:37], v[50:53], v[2:17]
	s_nop 11
	v_mul_f32_e32 v0, v30, v2
	v_mul_f32_e32 v2, v31, v3
	v_mul_f32_e32 v3, v33, v5
	v_cvt_pk_bf16_f32 v2, v0, v2
	v_mul_f32_e32 v0, v32, v4
	v_cvt_pk_bf16_f32 v3, v0, v3
	v_lshl_add_u64 v[4:5], v[106:107], 0, v[110:111]
	global_store_dwordx2 v[4:5], v[2:3], off
	v_mul_f32_e32 v0, v26, v6
	v_mul_f32_e32 v2, v27, v7
	v_mul_f32_e32 v3, v29, v9
	v_cvt_pk_bf16_f32 v2, v0, v2
	v_mul_f32_e32 v0, v28, v8
	v_cvt_pk_bf16_f32 v3, v0, v3
	v_lshl_add_u64 v[4:5], v[106:107], 0, v[112:113]
	global_store_dwordx2 v[4:5], v[2:3], off
	v_mul_f32_e32 v0, v22, v10
	v_mul_f32_e32 v2, v23, v11
	v_mul_f32_e32 v3, v25, v13
	v_cvt_pk_bf16_f32 v2, v0, v2
	v_mul_f32_e32 v0, v24, v12
	v_cvt_pk_bf16_f32 v3, v0, v3
	v_lshl_add_u64 v[4:5], v[106:107], 0, v[114:115]
	global_store_dwordx2 v[4:5], v[2:3], off
	v_mul_f32_e32 v0, v18, v14
	v_mul_f32_e32 v2, v19, v15
	v_mul_f32_e32 v3, v21, v17
	v_cvt_pk_bf16_f32 v2, v0, v2
	v_mul_f32_e32 v0, v20, v16
	v_cvt_pk_bf16_f32 v3, v0, v3

.Lpw_skip2:
.LBB0_227:
	s_or_b64 exec, exec, s[40:41]
	v_add_u32_e32 v54, s95, v83
	v_min_i32_e32 v54, 1, v54
	v_add_u32_e32 v54, 1, v54
	v_cvt_f32_i32_e32 v54, v54
	s_waitcnt vmcnt(24)
	v_cndmask_b32_e32 v9, 0, v9, vcc
	s_waitcnt vmcnt(8)
	v_cndmask_b32_e64 v0, 0, v50, s[34:35]
	v_cndmask_b32_e64 v10, 0, v10, s[0:1]
	v_rcp_iflag_f32_e32 v54, v54
	v_lshlrev_b32_e32 v50, 16, v9
	v_and_b32_e32 v9, 0xffff0000, v9
	v_add_f32_e32 v51, 0, v50
	v_add_f32_e32 v52, 0, v9
	v_lshlrev_b32_e32 v53, 16, v10
	v_and_b32_e32 v10, 0xffff0000, v10
	v_add_f32_e32 v51, v51, v53
	v_add_f32_e32 v52, v52, v10
	v_fma_f32 v55, v54, v51, -v53
	v_fma_f32 v54, v54, v52, -v10
	v_sub_f32_e32 v9, v52, v9
	v_add_u32_e32 v52, s95, v127
	v_min_i32_e32 v52, 1, v52
	v_add_u32_e32 v52, 1, v52
	v_cvt_f32_i32_e32 v52, v52
	v_cndmask_b32_e64 v11, v11, 0, s[2:3]
	v_sub_f32_e32 v50, v51, v50
	v_lshlrev_b32_e32 v51, 16, v11
	v_rcp_iflag_f32_e32 v52, v52
	v_and_b32_e32 v11, 0xffff0000, v11
	v_cvt_pk_bf16_f32 v54, v55, v54
	v_add_u32_e32 v168, 0, v145
	v_add_f32_e32 v50, v50, v51
	v_add_f32_e32 v9, v9, v11
	s_waitcnt lgkmcnt(0)
	s_barrier
	ds_write_b32 v168, v54 offset:34816
	v_fma_f32 v54, v52, v50, -v51
	v_fma_f32 v52, v52, v9, -v11
	v_cvt_pk_bf16_f32 v52, v54, v52
	v_add_u32_e32 v169, 0, v146
	ds_write_b32 v169, v52 offset:34816
	v_add_u32_e32 v52, s95, v128
	v_min_i32_e32 v52, 1, v52
	v_add_u32_e32 v52, 1, v52
	v_cvt_f32_i32_e32 v52, v52
	v_cndmask_b32_e64 v12, 0, v12, s[6:7]
	v_sub_f32_e32 v50, v50, v53
	v_sub_f32_e32 v9, v9, v10
	v_rcp_iflag_f32_e32 v52, v52
	v_lshlrev_b32_e32 v10, 16, v12
	v_add_f32_e32 v50, v50, v10
	v_and_b32_e32 v12, 0xffff0000, v12
	v_fma_f32 v53, v52, v50, -v10
	v_sub_f32_e32 v50, v50, v51
	v_add_u32_e32 v51, s95, v129
	v_min_i32_e32 v51, 1, v51
	v_add_u32_e32 v51, 1, v51
	v_cvt_f32_i32_e32 v51, v51
	v_cndmask_b32_e64 v13, 0, v13, s[8:9]
	v_add_f32_e32 v9, v9, v12
	v_fma_f32 v52, v52, v9, -v12
	v_rcp_iflag_f32_e32 v51, v51
	v_sub_f32_e32 v9, v9, v11
	v_lshlrev_b32_e32 v11, 16, v13
	v_cvt_pk_bf16_f32 v52, v53, v52
	v_add_u32_e32 v170, 0, v147
	v_add_f32_e32 v50, v50, v11
	ds_write_b32 v170, v52 offset:34816
	v_fma_f32 v52, v51, v50, -v11
	v_sub_f32_e32 v10, v50, v10
	v_add_u32_e32 v50, s95, v130
	v_min_i32_e32 v50, 1, v50
	v_add_u32_e32 v50, 1, v50
	v_cvt_f32_i32_e32 v50, v50
	v_and_b32_e32 v13, 0xffff0000, v13
	v_cndmask_b32_e64 v14, 0, v14, s[10:11]
	v_add_f32_e32 v9, v9, v13
	v_rcp_iflag_f32_e32 v50, v50
	v_fma_f32 v51, v51, v9, -v13
	v_sub_f32_e32 v9, v9, v12
	v_lshlrev_b32_e32 v12, 16, v14
	v_and_b32_e32 v14, 0xffff0000, v14
	v_cndmask_b32_e64 v15, 0, v15, s[12:13]
	v_cvt_pk_bf16_f32 v51, v52, v51
	v_add_u32_e32 v171, 0, v148
	v_add_f32_e32 v10, v10, v12
	v_add_f32_e32 v9, v9, v14
	ds_write_b32 v171, v51 offset:34816
	v_fma_f32 v51, v50, v10, -v12
	v_fma_f32 v50, v50, v9, -v14
	v_sub_f32_e32 v10, v10, v11
	v_sub_f32_e32 v9, v9, v13
	v_lshlrev_b32_e32 v11, 16, v15
	v_and_b32_e32 v13, 0xffff0000, v15
	v_add_u32_e32 v15, s95, v131
	v_min_i32_e32 v15, 1, v15
	v_add_u32_e32 v15, 1, v15
	v_cvt_f32_i32_e32 v15, v15
	v_cvt_pk_bf16_f32 v50, v51, v50
	v_add_u32_e32 v172, 0, v149
	v_add_f32_e32 v10, v10, v11
	v_rcp_iflag_f32_e32 v15, v15
	v_add_f32_e32 v9, v9, v13
	ds_write_b32 v172, v50 offset:34816
	v_add_u32_e32 v173, 0, v150
	v_fma_f32 v50, v15, v10, -v11
	v_fma_f32 v15, v15, v9, -v13
	v_cvt_pk_bf16_f32 v15, v50, v15
	ds_write_b32 v173, v15 offset:34816
	v_add_u32_e32 v15, s95, v132
	v_min_i32_e32 v15, 1, v15
	v_add_u32_e32 v15, 1, v15
	v_cvt_f32_i32_e32 v15, v15
	v_cndmask_b32_e64 v16, 0, v16, s[14:15]
	v_sub_f32_e32 v10, v10, v12
	v_sub_f32_e32 v9, v9, v14
	v_rcp_iflag_f32_e32 v15, v15
	v_lshlrev_b32_e32 v12, 16, v16
	v_and_b32_e32 v14, 0xffff0000, v16
	v_add_f32_e32 v10, v10, v12
	v_add_f32_e32 v9, v9, v14
	v_fma_f32 v16, v15, v10, -v12
	v_fma_f32 v15, v15, v9, -v14
	v_cvt_pk_bf16_f32 v15, v16, v15
	v_add_u32_e32 v174, 0, v151
	ds_write_b32 v174, v15 offset:34816
	v_add_u32_e32 v15, s95, v133
	v_min_i32_e32 v15, 1, v15
	v_add_u32_e32 v15, 1, v15
	v_cvt_f32_i32_e32 v15, v15
	v_cndmask_b32_e64 v17, 0, v17, s[16:17]
	v_sub_f32_e32 v10, v10, v11
	v_sub_f32_e32 v9, v9, v13
	v_rcp_iflag_f32_e32 v15, v15
	v_lshlrev_b32_e32 v11, 16, v17
	v_and_b32_e32 v13, 0xffff0000, v17
	v_add_f32_e32 v10, v10, v11
	v_add_f32_e32 v9, v9, v13
	v_fma_f32 v16, v15, v10, -v11
	v_fma_f32 v15, v15, v9, -v13
	v_sub_f32_e32 v9, v9, v14
	v_add_u32_e32 v14, s95, v134
	v_min_i32_e32 v14, 1, v14
	v_add_u32_e32 v14, 1, v14
	v_cvt_f32_i32_e32 v14, v14
	v_cndmask_b32_e64 v8, 0, v8, s[18:19]
	v_sub_f32_e32 v10, v10, v12
	v_lshlrev_b32_e32 v12, 16, v8
	v_rcp_iflag_f32_e32 v14, v14
	v_and_b32_e32 v8, 0xffff0000, v8
	v_cvt_pk_bf16_f32 v15, v16, v15
	v_add_u32_e32 v175, 0, v152
	v_add_f32_e32 v10, v10, v12
	v_add_f32_e32 v9, v9, v8
	ds_write_b32 v175, v15 offset:34816
	v_fma_f32 v15, v14, v10, -v12
	v_fma_f32 v14, v14, v9, -v8
	v_sub_f32_e32 v9, v9, v13
	v_add_u32_e32 v13, s95, v135
	v_min_i32_e32 v13, 1, v13
	v_add_u32_e32 v13, 1, v13
	v_cvt_f32_i32_e32 v13, v13
	v_cndmask_b32_e64 v7, 0, v7, s[20:21]
	v_sub_f32_e32 v10, v10, v11
	v_lshlrev_b32_e32 v11, 16, v7
	v_rcp_iflag_f32_e32 v13, v13
	v_cvt_pk_bf16_f32 v14, v15, v14
	v_add_u32_e32 v176, 0, v153
	v_add_f32_e32 v10, v10, v11
	ds_write_b32 v176, v14 offset:34816
	v_fma_f32 v14, v13, v10, -v11
	v_sub_f32_e32 v10, v10, v12
	v_add_u32_e32 v12, s95, v136
	v_min_i32_e32 v12, 1, v12
	v_add_u32_e32 v12, 1, v12
	v_cvt_f32_i32_e32 v12, v12
	v_and_b32_e32 v7, 0xffff0000, v7
	v_cndmask_b32_e64 v6, 0, v6, s[22:23]
	v_add_f32_e32 v9, v9, v7
	v_rcp_iflag_f32_e32 v12, v12
	v_fma_f32 v13, v13, v9, -v7
	v_sub_f32_e32 v8, v9, v8
	v_lshlrev_b32_e32 v9, 16, v6
	v_cvt_pk_bf16_f32 v13, v14, v13
	v_add_u32_e32 v177, 0, v154
	v_add_f32_e32 v10, v10, v9
	ds_write_b32 v177, v13 offset:34816
	v_fma_f32 v13, v12, v10, -v9
	v_sub_f32_e32 v10, v10, v11
	v_add_u32_e32 v11, s95, v137
	v_min_i32_e32 v11, 1, v11
	v_add_u32_e32 v11, 1, v11
	v_cvt_f32_i32_e32 v11, v11
	v_and_b32_e32 v6, 0xffff0000, v6
	v_cndmask_b32_e64 v5, 0, v5, s[24:25]
	v_add_f32_e32 v8, v8, v6
	v_rcp_iflag_f32_e32 v11, v11
	v_fma_f32 v12, v12, v8, -v6
	v_sub_f32_e32 v7, v8, v7
	v_lshlrev_b32_e32 v8, 16, v5
	v_cvt_pk_bf16_f32 v12, v13, v12
	v_add_u32_e32 v178, 0, v155
	v_add_f32_e32 v10, v10, v8
	ds_write_b32 v178, v12 offset:34816
	v_fma_f32 v12, v11, v10, -v8
	v_sub_f32_e32 v9, v10, v9
	v_add_u32_e32 v10, s95, v138
	v_min_i32_e32 v10, 1, v10
	v_add_u32_e32 v10, 1, v10
	v_cvt_f32_i32_e32 v10, v10
	v_and_b32_e32 v5, 0xffff0000, v5
	v_cndmask_b32_e64 v4, 0, v4, s[26:27]
	v_add_f32_e32 v7, v7, v5
	v_rcp_iflag_f32_e32 v10, v10
	v_fma_f32 v11, v11, v7, -v5
	v_sub_f32_e32 v6, v7, v6
	v_lshlrev_b32_e32 v7, 16, v4
	v_cvt_pk_bf16_f32 v11, v12, v11
	v_add_u32_e32 v179, 0, v156
	v_add_f32_e32 v9, v9, v7
	ds_write_b32 v179, v11 offset:34816
	v_fma_f32 v11, v10, v9, -v7
	v_sub_f32_e32 v8, v9, v8
	v_add_u32_e32 v9, s95, v139
	v_min_i32_e32 v9, 1, v9
	v_add_u32_e32 v9, 1, v9
	v_cvt_f32_i32_e32 v9, v9
	v_and_b32_e32 v4, 0xffff0000, v4
	v_cndmask_b32_e64 v3, 0, v3, s[28:29]
	v_add_f32_e32 v6, v6, v4
	v_rcp_iflag_f32_e32 v9, v9
	v_fma_f32 v10, v10, v6, -v4
	v_sub_f32_e32 v5, v6, v5
	v_lshlrev_b32_e32 v6, 16, v3
	v_cvt_pk_bf16_f32 v10, v11, v10
	v_add_u32_e32 v180, 0, v157
	v_add_f32_e32 v8, v8, v6
	ds_write_b32 v180, v10 offset:34816
	v_fma_f32 v10, v9, v8, -v6
	v_sub_f32_e32 v7, v8, v7
	v_add_u32_e32 v8, s95, v140
	v_min_i32_e32 v8, 1, v8
	v_add_u32_e32 v8, 1, v8
	v_cvt_f32_i32_e32 v8, v8
	v_and_b32_e32 v3, 0xffff0000, v3
	v_cndmask_b32_e64 v2, 0, v2, s[38:39]
	v_add_f32_e32 v5, v5, v3
	v_rcp_iflag_f32_e32 v8, v8
	v_fma_f32 v9, v9, v5, -v3
	v_sub_f32_e32 v4, v5, v4
	v_lshlrev_b32_e32 v5, 16, v2
	v_and_b32_e32 v2, 0xffff0000, v2
	v_add_f32_e32 v7, v7, v5
	v_add_f32_e32 v4, v4, v2
	v_fma_f32 v5, v8, v7, -v5
	v_fma_f32 v2, v8, v4, -v2
	v_cvt_pk_bf16_f32 v2, v5, v2
	v_add_u32_e32 v5, s95, v141
	v_min_i32_e32 v5, 1, v5
	v_add_u32_e32 v5, 1, v5
	v_cvt_f32_i32_e32 v5, v5
	v_add_u32_e32 v181, 0, v158
	v_add_u32_e32 v182, 0, v159
	s_or_b32 s0, s94, 0x80
	v_rcp_iflag_f32_e32 v5, v5
	v_cvt_pk_bf16_f32 v9, v10, v9
	ds_write_b32 v181, v9 offset:34816
	ds_write_b32 v182, v2 offset:34816
	v_sub_f32_e32 v2, v7, v6
	v_sub_f32_e32 v3, v4, v3
	v_lshlrev_b32_e32 v4, 16, v0
	v_and_b32_e32 v0, 0xffff0000, v0
	s_xor_b32 s1, s95, 0xffffff7f
	s_mul_i32 s2, s0, 0x1e00
	v_add_f32_e32 v2, v2, v4
	v_add_f32_e32 v3, v3, v0
	s_mul_hi_i32 s3, s0, 0x1e00
	s_add_u32 s2, s91, s2
	v_fma_f32 v2, v5, v2, -v4
	v_fma_f32 v0, v5, v3, -v0
	s_addc_u32 s3, s92, s3
	v_mov_b32_e32 v105, v1
	v_cvt_pk_bf16_f32 v0, v2, v0
	v_add_u32_e32 v183, 0, v160
	v_cmp_lt_i32_e32 vcc, s1, v141
	v_lshl_add_u64 v[2:3], s[2:3], 0, v[104:105]
	s_mov_b64 s[2:3], 0x1420
	ds_write_b32 v183, v0 offset:34816
	v_lshl_add_u64 v[2:3], v[2:3], 0, s[2:3]
	v_cndmask_b32_e32 v0, 0, v141, vcc
	s_movk_i32 s6, 0x1e00
	v_mad_i64_i32 v[4:5], s[2:3], v0, s6, v[2:3]
	global_load_dword v0, v[4:5], off
	v_add_u32_e32 v186, v144, v143
	v_add_u32_e32 v185, v144, v161
	v_mov_b32_e32 v103, v1
	v_add_u32_e32 v184, v144, v163
	v_lshlrev_b32_e32 v116, 1, v98
	v_mov_b32_e32 v117, v1
	s_mov_b64 s[36:37], 0
	s_waitcnt vmcnt(0)
	v_cndmask_b32_e32 v105, 0, v0, vcc
	v_cmp_lt_i32_e32 vcc, s1, v126
	v_mov_b32_e32 v212, 0
	s_nop 0
	v_cndmask_b32_e32 v0, 0, v126, vcc
	v_mad_i64_i32 v[4:5], s[2:3], v0, s6, v[2:3]
	s_and_saveexec_b64 s[98:99], vcc
	global_load_dword v212, v[4:5], off
	s_mov_b64 exec, s[98:99]
	v_cmp_lt_i32_e32 vcc, s1, v83
	v_mov_b32_e32 v213, 0
	s_nop 0
	v_cndmask_b32_e32 v0, 0, v83, vcc
	v_mad_i64_i32 v[4:5], s[2:3], v0, s6, v[2:3]
	s_and_saveexec_b64 s[98:99], vcc
	global_load_dword v213, v[4:5], off
	s_mov_b64 exec, s[98:99]
	v_cmp_gt_i32_e32 vcc, s1, v83
	s_nop 1
	v_cndmask_b32_e64 v0, v127, 0, vcc
	v_mad_i64_i32 v[4:5], s[2:3], v0, s6, v[2:3]
	global_load_dword v0, v[4:5], off
	s_waitcnt vmcnt(0)
	v_cndmask_b32_e64 v191, v0, 0, vcc
	v_cmp_lt_i32_e32 vcc, s1, v128
	v_mov_b32_e32 v211, 0
	s_nop 0
	v_cndmask_b32_e32 v0, 0, v128, vcc
	v_mad_i64_i32 v[4:5], s[2:3], v0, s6, v[2:3]
	s_and_saveexec_b64 s[98:99], vcc
	global_load_dword v211, v[4:5], off
	s_mov_b64 exec, s[98:99]
	v_cmp_lt_i32_e32 vcc, s1, v129
	v_mov_b32_e32 v210, 0
	s_nop 0
	v_cndmask_b32_e32 v0, 0, v129, vcc
	v_mad_i64_i32 v[4:5], s[2:3], v0, s6, v[2:3]
	s_and_saveexec_b64 s[98:99], vcc
	global_load_dword v210, v[4:5], off
	s_mov_b64 exec, s[98:99]
	v_cmp_lt_i32_e32 vcc, s1, v130
	v_mov_b32_e32 v209, 0
	s_nop 0
	v_cndmask_b32_e32 v0, 0, v130, vcc
	v_mad_i64_i32 v[4:5], s[2:3], v0, s6, v[2:3]
	s_and_saveexec_b64 s[98:99], vcc
	global_load_dword v209, v[4:5], off
	s_mov_b64 exec, s[98:99]
	v_cmp_lt_i32_e32 vcc, s1, v131
	v_mov_b32_e32 v208, 0
	s_nop 0
	v_cndmask_b32_e32 v0, 0, v131, vcc
	v_mad_i64_i32 v[4:5], s[2:3], v0, s6, v[2:3]
	s_and_saveexec_b64 s[98:99], vcc
	global_load_dword v208, v[4:5], off
	s_mov_b64 exec, s[98:99]
	v_cmp_lt_i32_e32 vcc, s1, v132
	v_mov_b32_e32 v207, 0
	s_nop 0
	v_cndmask_b32_e32 v0, 0, v132, vcc
	v_mad_i64_i32 v[4:5], s[2:3], v0, s6, v[2:3]
	s_and_saveexec_b64 s[98:99], vcc
	global_load_dword v207, v[4:5], off
	s_mov_b64 exec, s[98:99]
	v_cmp_lt_i32_e32 vcc, s1, v133
	v_mov_b32_e32 v206, 0
	s_nop 0
	v_cndmask_b32_e32 v0, 0, v133, vcc
	v_mad_i64_i32 v[4:5], s[2:3], v0, s6, v[2:3]
	s_and_saveexec_b64 s[98:99], vcc
	global_load_dword v206, v[4:5], off
	s_mov_b64 exec, s[98:99]
	v_cmp_lt_i32_e32 vcc, s1, v134
	v_mov_b32_e32 v205, 0
	s_nop 0
	v_cndmask_b32_e32 v0, 0, v134, vcc
	v_mad_i64_i32 v[4:5], s[2:3], v0, s6, v[2:3]
	s_and_saveexec_b64 s[98:99], vcc
	global_load_dword v205, v[4:5], off
	s_mov_b64 exec, s[98:99]
	v_cmp_lt_i32_e32 vcc, s1, v135
	v_mov_b32_e32 v204, 0
	s_nop 0
	v_cndmask_b32_e32 v0, 0, v135, vcc
	v_mad_i64_i32 v[4:5], s[2:3], v0, s6, v[2:3]
	s_and_saveexec_b64 s[98:99], vcc
	global_load_dword v204, v[4:5], off
	s_mov_b64 exec, s[98:99]
	v_cmp_lt_i32_e32 vcc, s1, v136
	v_mov_b32_e32 v192, 0
	s_nop 0
	v_cndmask_b32_e32 v0, 0, v136, vcc
	v_mad_i64_i32 v[4:5], s[2:3], v0, s6, v[2:3]
	s_and_saveexec_b64 s[98:99], vcc
	global_load_dword v192, v[4:5], off
	s_mov_b64 exec, s[98:99]
	v_cmp_lt_i32_e32 vcc, s1, v137
	v_mov_b32_e32 v190, 0
	s_nop 0
	v_cndmask_b32_e32 v0, 0, v137, vcc
	v_mad_i64_i32 v[4:5], s[2:3], v0, s6, v[2:3]
	s_and_saveexec_b64 s[98:99], vcc
	global_load_dword v190, v[4:5], off
	s_mov_b64 exec, s[98:99]
	v_cmp_lt_i32_e32 vcc, s1, v138
	v_mov_b32_e32 v189, 0
	s_nop 0
	v_cndmask_b32_e32 v0, 0, v138, vcc
	v_mad_i64_i32 v[4:5], s[2:3], v0, s6, v[2:3]
	s_and_saveexec_b64 s[98:99], vcc
	global_load_dword v189, v[4:5], off
	s_mov_b64 exec, s[98:99]
	v_cmp_lt_i32_e32 vcc, s1, v139
	v_mov_b32_e32 v188, 0
	s_nop 0
	v_cndmask_b32_e32 v0, 0, v139, vcc
	v_mad_i64_i32 v[4:5], s[2:3], v0, s6, v[2:3]
	s_and_saveexec_b64 s[98:99], vcc
	global_load_dword v188, v[4:5], off
	s_mov_b64 exec, s[98:99]
	v_cmp_lt_i32_e32 vcc, s1, v140
	s_and_b32 s1, s0, 0xf80
	s_nop 0
	v_cndmask_b32_e32 v0, 0, v140, vcc
	v_mad_i64_i32 v[2:3], s[2:3], v0, s6, v[2:3]
	global_load_dword v0, v[2:3], off
	v_add_u32_e32 v2, s94, v142
	v_ashrrev_i32_e32 v3, 31, v2
	v_lshlrev_b64 v[2:3], 12, v[2:3]
	s_waitcnt lgkmcnt(0)
	s_barrier
	v_lshl_add_u64 v[2:3], s[70:71], 0, v[2:3]
	s_mov_b64 s[2:3], 0x26000800
	ds_read_b128 v[74:77], v186 offset:34816
	ds_read_b128 v[78:81], v186 offset:34848
	ds_read_b128 v[70:73], v186 offset:34880
	ds_read_b128 v[66:69], v186 offset:34912
	ds_read_b128 v[62:65], v186 offset:34944
	ds_read_b128 v[58:61], v186 offset:34976
	ds_read_b128 v[54:57], v186 offset:35008
	ds_read_b128 v[50:53], v186 offset:35040
	v_lshl_add_u64 v[106:107], v[2:3], 0, s[2:3]
	ds_read_b128 v[2:5], v185
	ds_read_b128 v[108:111], v185 offset:32
	ds_read_b128 v[228:231], v185 offset:64
	ds_read_b128 v[242:245], v185 offset:96
	s_waitcnt lgkmcnt(3)
	v_mfma_f32_32x32x16_bf16 v[2:17], v[2:5], v[74:77], 0
	s_waitcnt vmcnt(0)
	v_cndmask_b32_e32 v187, 0, v0, vcc
	s_waitcnt lgkmcnt(2)
	v_mfma_f32_32x32x16_bf16 v[2:17], v[108:111], v[78:81], v[2:17]
	ds_read_b128 v[108:111], v185 offset:128
	s_waitcnt lgkmcnt(2)
	v_mfma_f32_32x32x16_bf16 v[2:17], v[228:231], v[70:73], v[2:17]
	ds_read_b128 v[228:231], v185 offset:160
	s_waitcnt lgkmcnt(2)
	v_mfma_f32_32x32x16_bf16 v[2:17], v[242:245], v[66:69], v[2:17]
	ds_read_b128 v[242:245], v185 offset:192
	s_waitcnt lgkmcnt(2)
	v_mfma_f32_32x32x16_bf16 v[2:17], v[108:111], v[62:65], v[2:17]
	ds_read_b128 v[108:111], v185 offset:224
	s_waitcnt lgkmcnt(2)
	v_mfma_f32_32x32x16_bf16 v[2:17], v[228:231], v[58:61], v[2:17]
	s_waitcnt lgkmcnt(1)
	v_mfma_f32_32x32x16_bf16 v[2:17], v[242:245], v[54:57], v[2:17]
	s_waitcnt lgkmcnt(0)
	v_mfma_f32_32x32x16_bf16 v[2:17], v[108:111], v[50:53], v[2:17]
	v_lshlrev_b32_e32 v108, 1, v90
	v_mov_b32_e32 v109, v1
	v_lshlrev_b32_e32 v110, 1, v92
	v_mov_b32_e32 v111, v1
	s_nop 7
	v_mul_f32_e32 v0, v46, v2
	v_mul_f32_e32 v2, v47, v3
	v_cvt_pk_bf16_f32 v2, v0, v2
	v_mul_f32_e32 v0, v48, v4
	v_mul_f32_e32 v3, v49, v5
	v_cvt_pk_bf16_f32 v3, v0, v3
	v_lshlrev_b32_e32 v0, 1, v88
	v_lshl_add_u64 v[4:5], v[106:107], 0, v[0:1]
	global_store_dwordx2 v[4:5], v[2:3], off
	v_mul_f32_e32 v2, v42, v6
	v_mul_f32_e32 v3, v43, v7
	v_cvt_pk_bf16_f32 v2, v2, v3
	v_mul_f32_e32 v3, v44, v8
	v_mul_f32_e32 v4, v45, v9
	v_cvt_pk_bf16_f32 v3, v3, v4
	v_lshl_add_u64 v[4:5], v[106:107], 0, v[108:109]
	global_store_dwordx2 v[4:5], v[2:3], off
	v_mul_f32_e32 v2, v38, v10
	v_mul_f32_e32 v3, v39, v11
	v_cvt_pk_bf16_f32 v2, v2, v3
	v_mul_f32_e32 v3, v40, v12
	v_mul_f32_e32 v4, v41, v13
	v_cvt_pk_bf16_f32 v3, v3, v4
	v_lshl_add_u64 v[4:5], v[106:107], 0, v[110:111]
	global_store_dwordx2 v[4:5], v[2:3], off
	v_mul_f32_e32 v2, v34, v14
	v_mul_f32_e32 v3, v35, v15
	v_cvt_pk_bf16_f32 v2, v2, v3
	v_mul_f32_e32 v3, v36, v16
	v_mul_f32_e32 v4, v37, v17
	v_cvt_pk_bf16_f32 v3, v3, v4
	v_lshl_add_u64 v[4:5], v[106:107], 0, v[102:103]
	global_store_dwordx2 v[4:5], v[2:3], off
	ds_read_b128 v[228:231], v184
	ds_read_b128 v[242:245], v184 offset:32
	ds_read_b128 v[246:249], v184 offset:64
	s_waitcnt lgkmcnt(2)
	v_mfma_f32_32x32x16_bf16 v[2:17], v[228:231], v[74:77], 0
	ds_read_b128 v[228:231], v184 offset:96
	s_waitcnt lgkmcnt(2)
	v_mfma_f32_32x32x16_bf16 v[2:17], v[242:245], v[78:81], v[2:17]
	ds_read_b128 v[242:245], v184 offset:128
	v_lshlrev_b32_e32 v112, 1, v94
	v_mov_b32_e32 v113, v1
	v_lshlrev_b32_e32 v114, 1, v96
	v_mov_b32_e32 v115, v1
	s_waitcnt lgkmcnt(2)
	v_mfma_f32_32x32x16_bf16 v[2:17], v[246:249], v[70:73], v[2:17]
	ds_read_b128 v[246:249], v184 offset:160
	s_waitcnt lgkmcnt(2)
	v_mfma_f32_32x32x16_bf16 v[2:17], v[228:231], v[66:69], v[2:17]
	ds_read_b128 v[228:231], v184 offset:192
	s_waitcnt lgkmcnt(2)
	v_mfma_f32_32x32x16_bf16 v[2:17], v[242:245], v[62:65], v[2:17]
	ds_read_b128 v[242:245], v184 offset:224
	s_waitcnt lgkmcnt(2)
	v_mfma_f32_32x32x16_bf16 v[2:17], v[246:249], v[58:61], v[2:17]
	s_waitcnt lgkmcnt(1)
	v_mfma_f32_32x32x16_bf16 v[2:17], v[228:231], v[54:57], v[2:17]
	s_waitcnt lgkmcnt(0)
	v_mfma_f32_32x32x16_bf16 v[2:17], v[242:245], v[50:53], v[2:17]
	s_nop 11
	v_mul_f32_e32 v2, v30, v2
	v_mul_f32_e32 v3, v31, v3
	v_cvt_pk_bf16_f32 v2, v2, v3
	v_mul_f32_e32 v3, v32, v4
	v_mul_f32_e32 v4, v33, v5
	v_cvt_pk_bf16_f32 v3, v3, v4
	v_lshl_add_u64 v[4:5], v[106:107], 0, v[112:113]
	global_store_dwordx2 v[4:5], v[2:3], off
	v_mul_f32_e32 v2, v26, v6
	v_mul_f32_e32 v3, v27, v7
	v_cvt_pk_bf16_f32 v2, v2, v3
	v_mul_f32_e32 v3, v28, v8
	v_mul_f32_e32 v4, v29, v9
	v_cvt_pk_bf16_f32 v3, v3, v4
	v_lshl_add_u64 v[4:5], v[106:107], 0, v[114:115]
	v_add_u32_e32 v8, s1, v83
	global_store_dwordx2 v[4:5], v[2:3], off
	v_mul_f32_e32 v2, v22, v10
	v_mul_f32_e32 v3, v23, v11
	v_min_i32_e32 v8, 1, v8
	v_cvt_pk_bf16_f32 v2, v2, v3
	v_mul_f32_e32 v3, v24, v12
	v_mul_f32_e32 v4, v25, v13
	v_add_u32_e32 v8, 1, v8
	v_cvt_pk_bf16_f32 v3, v3, v4
	v_lshl_add_u64 v[4:5], v[106:107], 0, v[116:117]
	v_cvt_f32_i32_e32 v8, v8
	global_store_dwordx2 v[4:5], v[2:3], off
	v_mul_f32_e32 v2, v18, v14
	v_mul_f32_e32 v3, v19, v15
	v_cvt_pk_bf16_f32 v2, v2, v3
	v_mul_f32_e32 v3, v20, v16
	v_mul_f32_e32 v4, v21, v17
	v_cvt_pk_bf16_f32 v3, v3, v4
	v_lshlrev_b32_e32 v4, 1, v100
	v_mov_b32_e32 v5, v1
	v_lshl_add_u64 v[4:5], v[106:107], 0, v[4:5]
	v_rcp_iflag_f32_e32 v8, v8
	global_store_dwordx2 v[4:5], v[2:3], off
	v_lshlrev_b32_e32 v2, 16, v212
	v_and_b32_e32 v3, 0xffff0000, v212
	v_add_f32_e32 v4, 0, v2
	v_add_f32_e32 v5, 0, v3
	v_lshlrev_b32_e32 v6, 16, v213
	v_and_b32_e32 v7, 0xffff0000, v213
	v_add_f32_e32 v4, v4, v6
	v_add_f32_e32 v5, v5, v7
	v_fma_f32 v9, v8, v4, -v6
	v_fma_f32 v8, v8, v5, -v7
	v_cvt_pk_bf16_f32 v8, v9, v8
	s_waitcnt lgkmcnt(0)
	s_barrier
	ds_write_b32 v168, v8 offset:34816
	v_add_u32_e32 v8, s1, v127
	v_min_i32_e32 v8, 1, v8
	v_add_u32_e32 v8, 1, v8
	v_cvt_f32_i32_e32 v8, v8
	v_sub_f32_e32 v2, v4, v2
	v_sub_f32_e32 v3, v5, v3
	v_lshlrev_b32_e32 v4, 16, v191
	v_rcp_iflag_f32_e32 v8, v8
	v_and_b32_e32 v5, 0xffff0000, v191
	v_add_f32_e32 v2, v2, v4
	v_add_f32_e32 v3, v3, v5
	v_fma_f32 v9, v8, v2, -v4
	v_fma_f32 v8, v8, v3, -v5
	v_cvt_pk_bf16_f32 v8, v9, v8
	ds_write_b32 v169, v8 offset:34816
	v_add_u32_e32 v8, s1, v128
	v_min_i32_e32 v8, 1, v8
	v_add_u32_e32 v8, 1, v8
	v_cvt_f32_i32_e32 v8, v8
	v_sub_f32_e32 v2, v2, v6
	v_sub_f32_e32 v3, v3, v7
	v_lshlrev_b32_e32 v6, 16, v211
	v_rcp_iflag_f32_e32 v8, v8
	v_and_b32_e32 v7, 0xffff0000, v211
	v_add_f32_e32 v2, v2, v6
	v_add_f32_e32 v3, v3, v7
	v_fma_f32 v9, v8, v2, -v6
	v_fma_f32 v8, v8, v3, -v7
	v_cvt_pk_bf16_f32 v8, v9, v8
	ds_write_b32 v170, v8 offset:34816
	v_add_u32_e32 v8, s1, v129
	v_min_i32_e32 v8, 1, v8
	v_add_u32_e32 v8, 1, v8
	v_cvt_f32_i32_e32 v8, v8
	v_sub_f32_e32 v2, v2, v4
	v_sub_f32_e32 v3, v3, v5
	v_lshlrev_b32_e32 v4, 16, v210
	v_rcp_iflag_f32_e32 v8, v8
	v_and_b32_e32 v5, 0xffff0000, v210
	v_add_f32_e32 v2, v2, v4
	v_add_f32_e32 v3, v3, v5
	v_fma_f32 v9, v8, v2, -v4
	v_fma_f32 v8, v8, v3, -v5
	v_cvt_pk_bf16_f32 v8, v9, v8
	ds_write_b32 v171, v8 offset:34816
	v_add_u32_e32 v8, s1, v130
	v_min_i32_e32 v8, 1, v8
	v_add_u32_e32 v8, 1, v8
	v_cvt_f32_i32_e32 v8, v8
	v_sub_f32_e32 v2, v2, v6
	v_sub_f32_e32 v3, v3, v7
	v_lshlrev_b32_e32 v6, 16, v209
	v_rcp_iflag_f32_e32 v8, v8
	v_and_b32_e32 v7, 0xffff0000, v209
	v_add_f32_e32 v2, v2, v6
	v_add_f32_e32 v3, v3, v7
	v_fma_f32 v9, v8, v2, -v6
	v_fma_f32 v8, v8, v3, -v7
	v_cvt_pk_bf16_f32 v8, v9, v8
	ds_write_b32 v172, v8 offset:34816
	v_add_u32_e32 v8, s1, v131
	v_min_i32_e32 v8, 1, v8
	v_add_u32_e32 v8, 1, v8
	v_cvt_f32_i32_e32 v8, v8
	v_sub_f32_e32 v2, v2, v4
	v_sub_f32_e32 v3, v3, v5
	v_lshlrev_b32_e32 v4, 16, v208
	v_rcp_iflag_f32_e32 v8, v8
	v_and_b32_e32 v5, 0xffff0000, v208
	v_add_f32_e32 v2, v2, v4
	v_add_f32_e32 v3, v3, v5
	v_fma_f32 v9, v8, v2, -v4
	v_fma_f32 v8, v8, v3, -v5
	v_cvt_pk_bf16_f32 v8, v9, v8
	ds_write_b32 v173, v8 offset:34816
	v_add_u32_e32 v8, s1, v132
	v_min_i32_e32 v8, 1, v8
	v_add_u32_e32 v8, 1, v8
	v_cvt_f32_i32_e32 v8, v8
	v_sub_f32_e32 v2, v2, v6
	v_sub_f32_e32 v3, v3, v7
	v_lshlrev_b32_e32 v6, 16, v207
	v_rcp_iflag_f32_e32 v8, v8
	v_and_b32_e32 v7, 0xffff0000, v207
	v_add_f32_e32 v2, v2, v6
	v_add_f32_e32 v3, v3, v7
	v_fma_f32 v9, v8, v2, -v6
	v_fma_f32 v8, v8, v3, -v7
	v_cvt_pk_bf16_f32 v8, v9, v8
	ds_write_b32 v174, v8 offset:34816
	v_add_u32_e32 v8, s1, v133
	v_min_i32_e32 v8, 1, v8
	v_add_u32_e32 v8, 1, v8
	v_cvt_f32_i32_e32 v8, v8
	v_sub_f32_e32 v2, v2, v4
	v_sub_f32_e32 v3, v3, v5
	v_lshlrev_b32_e32 v4, 16, v206
	v_rcp_iflag_f32_e32 v8, v8
	v_and_b32_e32 v5, 0xffff0000, v206
	v_add_f32_e32 v2, v2, v4
	v_add_f32_e32 v3, v3, v5
	v_fma_f32 v9, v8, v2, -v4
	v_fma_f32 v8, v8, v3, -v5
	v_cvt_pk_bf16_f32 v8, v9, v8
	ds_write_b32 v175, v8 offset:34816
	v_add_u32_e32 v8, s1, v134
	v_min_i32_e32 v8, 1, v8
	v_add_u32_e32 v8, 1, v8
	v_cvt_f32_i32_e32 v8, v8
	v_sub_f32_e32 v2, v2, v6
	v_sub_f32_e32 v3, v3, v7
	v_lshlrev_b32_e32 v6, 16, v205
	v_rcp_iflag_f32_e32 v8, v8
	v_and_b32_e32 v7, 0xffff0000, v205
	v_add_f32_e32 v2, v2, v6
	v_add_f32_e32 v3, v3, v7
	v_fma_f32 v9, v8, v2, -v6
	v_fma_f32 v8, v8, v3, -v7
	v_cvt_pk_bf16_f32 v8, v9, v8
	ds_write_b32 v176, v8 offset:34816
	v_add_u32_e32 v8, s1, v135
	v_min_i32_e32 v8, 1, v8
	v_add_u32_e32 v8, 1, v8
	v_cvt_f32_i32_e32 v8, v8
	v_sub_f32_e32 v2, v2, v4
	v_sub_f32_e32 v3, v3, v5
	v_lshlrev_b32_e32 v4, 16, v204
	v_rcp_iflag_f32_e32 v8, v8
	v_and_b32_e32 v5, 0xffff0000, v204
	v_add_f32_e32 v2, v2, v4
	v_add_f32_e32 v3, v3, v5
	v_fma_f32 v9, v8, v2, -v4
	v_fma_f32 v8, v8, v3, -v5
	v_cvt_pk_bf16_f32 v8, v9, v8
	ds_write_b32 v177, v8 offset:34816
	v_add_u32_e32 v8, s1, v136
	v_min_i32_e32 v8, 1, v8
	v_add_u32_e32 v8, 1, v8
	v_cvt_f32_i32_e32 v8, v8
	v_sub_f32_e32 v2, v2, v6
	v_sub_f32_e32 v3, v3, v7
	v_lshlrev_b32_e32 v6, 16, v192
	v_rcp_iflag_f32_e32 v8, v8
	v_and_b32_e32 v7, 0xffff0000, v192
	v_add_f32_e32 v2, v2, v6
	v_add_f32_e32 v3, v3, v7
	v_fma_f32 v9, v8, v2, -v6
	v_fma_f32 v8, v8, v3, -v7
	v_cvt_pk_bf16_f32 v8, v9, v8
	ds_write_b32 v178, v8 offset:34816
	v_add_u32_e32 v8, s1, v137
	v_min_i32_e32 v8, 1, v8
	v_add_u32_e32 v8, 1, v8
	v_cvt_f32_i32_e32 v8, v8
	v_sub_f32_e32 v2, v2, v4
	v_sub_f32_e32 v3, v3, v5
	v_lshlrev_b32_e32 v4, 16, v190
	v_rcp_iflag_f32_e32 v8, v8
	v_and_b32_e32 v5, 0xffff0000, v190
	v_add_f32_e32 v2, v2, v4
	v_add_f32_e32 v3, v3, v5
	v_fma_f32 v9, v8, v2, -v4
	v_fma_f32 v8, v8, v3, -v5
	v_cvt_pk_bf16_f32 v8, v9, v8
	ds_write_b32 v179, v8 offset:34816
	v_add_u32_e32 v8, s1, v138
	v_min_i32_e32 v8, 1, v8
	v_add_u32_e32 v8, 1, v8
	v_cvt_f32_i32_e32 v8, v8
	v_sub_f32_e32 v2, v2, v6
	v_sub_f32_e32 v3, v3, v7
	v_lshlrev_b32_e32 v6, 16, v189
	v_rcp_iflag_f32_e32 v8, v8
	v_and_b32_e32 v7, 0xffff0000, v189
	v_add_f32_e32 v2, v2, v6
	v_add_f32_e32 v3, v3, v7
	v_fma_f32 v9, v8, v2, -v6
	v_fma_f32 v8, v8, v3, -v7
	v_cvt_pk_bf16_f32 v8, v9, v8
	ds_write_b32 v180, v8 offset:34816
	v_add_u32_e32 v8, s1, v139
	v_min_i32_e32 v8, 1, v8
	v_add_u32_e32 v8, 1, v8
	v_cvt_f32_i32_e32 v8, v8
	v_sub_f32_e32 v2, v2, v4
	v_sub_f32_e32 v3, v3, v5
	v_lshlrev_b32_e32 v4, 16, v188
	v_rcp_iflag_f32_e32 v8, v8
	v_and_b32_e32 v5, 0xffff0000, v188
	v_add_f32_e32 v2, v2, v4
	v_add_f32_e32 v3, v3, v5
	v_fma_f32 v9, v8, v2, -v4
	v_fma_f32 v8, v8, v3, -v5
	v_cvt_pk_bf16_f32 v8, v9, v8
	ds_write_b32 v181, v8 offset:34816
	v_add_u32_e32 v8, s1, v140
	v_min_i32_e32 v8, 1, v8
	v_add_u32_e32 v8, 1, v8
	v_cvt_f32_i32_e32 v8, v8
	v_sub_f32_e32 v2, v2, v6
	v_lshlrev_b32_e32 v6, 16, v187
	v_sub_f32_e32 v3, v3, v7
	v_rcp_iflag_f32_e32 v8, v8
	v_and_b32_e32 v7, 0xffff0000, v187
	v_add_f32_e32 v2, v2, v6
	v_add_f32_e32 v3, v3, v7
	v_fma_f32 v6, v8, v2, -v6
	v_fma_f32 v7, v8, v3, -v7
	v_cvt_pk_bf16_f32 v6, v6, v7
	ds_write_b32 v182, v6 offset:34816
	v_add_u32_e32 v6, s1, v141
	v_min_i32_e32 v6, 1, v6
	v_add_u32_e32 v6, 1, v6
	v_cvt_f32_i32_e32 v6, v6
	v_sub_f32_e32 v2, v2, v4
	v_lshlrev_b32_e32 v4, 16, v105
	v_sub_f32_e32 v3, v3, v5
	v_rcp_iflag_f32_e32 v6, v6
	v_and_b32_e32 v5, 0xffff0000, v105
	v_add_f32_e32 v2, v2, v4
	v_add_f32_e32 v3, v3, v5
	v_fma_f32 v2, v6, v2, -v4
	v_fma_f32 v3, v6, v3, -v5
	v_cvt_pk_bf16_f32 v2, v2, v3
	ds_write_b32 v183, v2 offset:34816
	v_add_u32_e32 v2, s0, v142
	v_ashrrev_i32_e32 v3, 31, v2
	v_lshlrev_b64 v[2:3], 12, v[2:3]
	s_waitcnt lgkmcnt(0)
	s_barrier
	v_lshl_add_u64 v[2:3], s[70:71], 0, v[2:3]
	ds_read_b128 v[74:77], v186 offset:34816
	ds_read_b128 v[78:81], v186 offset:34848
	ds_read_b128 v[70:73], v186 offset:34880
	ds_read_b128 v[66:69], v186 offset:34912
	ds_read_b128 v[62:65], v186 offset:34944
	ds_read_b128 v[58:61], v186 offset:34976
	ds_read_b128 v[54:57], v186 offset:35008
	ds_read_b128 v[50:53], v186 offset:35040
	v_lshl_add_u64 v[106:107], v[2:3], 0, s[2:3]
	ds_read_b128 v[2:5], v185
	ds_read_b128 v[168:171], v185 offset:32
	ds_read_b128 v[228:231], v185 offset:64
	ds_read_b128 v[242:245], v185 offset:96
	s_waitcnt lgkmcnt(3)
	v_mfma_f32_32x32x16_bf16 v[2:17], v[2:5], v[74:77], 0
	s_waitcnt lgkmcnt(2)
	v_mfma_f32_32x32x16_bf16 v[2:17], v[168:171], v[78:81], v[2:17]
	ds_read_b128 v[168:171], v185 offset:128
	s_waitcnt lgkmcnt(2)
	v_mfma_f32_32x32x16_bf16 v[2:17], v[228:231], v[70:73], v[2:17]
	ds_read_b128 v[228:231], v185 offset:160
	s_waitcnt lgkmcnt(2)
	v_mfma_f32_32x32x16_bf16 v[2:17], v[242:245], v[66:69], v[2:17]
	ds_read_b128 v[242:245], v185 offset:192
	s_waitcnt lgkmcnt(2)
	v_mfma_f32_32x32x16_bf16 v[2:17], v[168:171], v[62:65], v[2:17]
	ds_read_b128 v[168:171], v185 offset:224
	s_waitcnt lgkmcnt(2)
	v_mfma_f32_32x32x16_bf16 v[2:17], v[228:231], v[58:61], v[2:17]
	s_waitcnt lgkmcnt(1)
	v_mfma_f32_32x32x16_bf16 v[2:17], v[242:245], v[54:57], v[2:17]
	s_waitcnt lgkmcnt(0)
	v_mfma_f32_32x32x16_bf16 v[2:17], v[168:171], v[50:53], v[2:17]
	s_nop 11
	v_mul_f32_e32 v2, v46, v2
	v_mul_f32_e32 v3, v47, v3
	v_cvt_pk_bf16_f32 v2, v2, v3
	v_mul_f32_e32 v3, v48, v4
	v_mul_f32_e32 v4, v49, v5
	v_cvt_pk_bf16_f32 v3, v3, v4
	v_lshl_add_u64 v[4:5], v[106:107], 0, v[0:1]
	global_store_dwordx2 v[4:5], v[2:3], off
	v_mul_f32_e32 v0, v42, v6
	v_mul_f32_e32 v2, v43, v7
	v_mul_f32_e32 v3, v45, v9
	v_cvt_pk_bf16_f32 v2, v0, v2
	v_mul_f32_e32 v0, v44, v8
	v_cvt_pk_bf16_f32 v3, v0, v3
	v_lshl_add_u64 v[4:5], v[106:107], 0, v[108:109]
	global_store_dwordx2 v[4:5], v[2:3], off
	v_mul_f32_e32 v0, v38, v10
	v_mul_f32_e32 v2, v39, v11
	v_mul_f32_e32 v3, v41, v13
	v_cvt_pk_bf16_f32 v2, v0, v2
	v_mul_f32_e32 v0, v40, v12
	v_cvt_pk_bf16_f32 v3, v0, v3
	v_lshl_add_u64 v[4:5], v[106:107], 0, v[110:111]
	global_store_dwordx2 v[4:5], v[2:3], off
	v_mul_f32_e32 v0, v34, v14
	v_mul_f32_e32 v2, v35, v15
	v_mul_f32_e32 v3, v37, v17
	v_lshl_add_u64 v[4:5], v[106:107], 0, v[102:103]
	v_cvt_pk_bf16_f32 v2, v0, v2
	v_mul_f32_e32 v0, v36, v16
	v_cvt_pk_bf16_f32 v3, v0, v3
	global_store_dwordx2 v[4:5], v[2:3], off
	ds_read_b128 v[2:5], v184
	ds_read_b128 v[34:37], v184 offset:32
	ds_read_b128 v[228:231], v184 offset:64
	ds_read_b128 v[242:245], v184 offset:96
	s_waitcnt lgkmcnt(3)
	v_mfma_f32_32x32x16_bf16 v[2:17], v[2:5], v[74:77], 0
	s_waitcnt lgkmcnt(2)
	v_mfma_f32_32x32x16_bf16 v[2:17], v[34:37], v[78:81], v[2:17]
	ds_read_b128 v[34:37], v184 offset:128
	s_waitcnt lgkmcnt(2)
	v_mfma_f32_32x32x16_bf16 v[2:17], v[228:231], v[70:73], v[2:17]
	ds_read_b128 v[228:231], v184 offset:160
	s_waitcnt lgkmcnt(2)
	v_mfma_f32_32x32x16_bf16 v[2:17], v[242:245], v[66:69], v[2:17]
	ds_read_b128 v[242:245], v184 offset:192
	s_waitcnt lgkmcnt(2)
	v_mfma_f32_32x32x16_bf16 v[2:17], v[34:37], v[62:65], v[2:17]
	ds_read_b128 v[34:37], v184 offset:224
	s_waitcnt lgkmcnt(2)
	v_mfma_f32_32x32x16_bf16 v[2:17], v[228:231], v[58:61], v[2:17]
	s_waitcnt lgkmcnt(1)
	v_mfma_f32_32x32x16_bf16 v[2:17], v[242:245], v[54:57], v[2:17]
	s_waitcnt lgkmcnt(0)
	v_mfma_f32_32x32x16_bf16 v[2:17], v[34:37], v[50:53], v[2:17]
	s_nop 11
	v_mul_f32_e32 v0, v30, v2
	v_mul_f32_e32 v2, v31, v3
	v_mul_f32_e32 v3, v33, v5
	v_cvt_pk_bf16_f32 v2, v0, v2
	v_mul_f32_e32 v0, v32, v4
	v_cvt_pk_bf16_f32 v3, v0, v3
	v_lshl_add_u64 v[4:5], v[106:107], 0, v[112:113]
	global_store_dwordx2 v[4:5], v[2:3], off
	v_mul_f32_e32 v0, v26, v6
	v_mul_f32_e32 v2, v27, v7
	v_mul_f32_e32 v3, v29, v9
	v_cvt_pk_bf16_f32 v2, v0, v2
	v_mul_f32_e32 v0, v28, v8
	v_cvt_pk_bf16_f32 v3, v0, v3
	v_lshl_add_u64 v[4:5], v[106:107], 0, v[114:115]
	global_store_dwordx2 v[4:5], v[2:3], off
	v_mul_f32_e32 v0, v22, v10
	v_mul_f32_e32 v2, v23, v11
	v_mul_f32_e32 v3, v25, v13
	v_cvt_pk_bf16_f32 v2, v0, v2
	v_mul_f32_e32 v0, v24, v12
	v_cvt_pk_bf16_f32 v3, v0, v3
	v_lshl_add_u64 v[4:5], v[106:107], 0, v[116:117]
	global_store_dwordx2 v[4:5], v[2:3], off
	v_mul_f32_e32 v0, v18, v14
	v_mul_f32_e32 v2, v19, v15
	v_mul_f32_e32 v3, v21, v17
	v_cvt_pk_bf16_f32 v2, v0, v2
	v_mul_f32_e32 v0, v20, v16
	v_cvt_pk_bf16_f32 v3, v0, v3

.Lpw_copy3:
	v_ashrrev_i32_e32 v232, 4, v118
	v_lshlrev_b32_e32 v250, 7, v232
	v_ashrrev_i32_e32 v251, 31, v250
	v_and_b32_e32 v233, 0x78, v89
	v_lshl_add_u64 v[250:251], v[250:251], 1, s[78:79]
	v_lshlrev_b32_e32 v0, 1, v233
	v_lshl_add_u64 v[250:251], v[250:251], 0, v[0:1]
	s_mov_b64 s[46:47], 0x2000
	global_load_dwordx4 v[228:231], v[250:251], off
	v_lshl_add_u64 v[250:251], v[250:251], 0, s[46:47]
	global_load_dwordx4 v[242:245], v[250:251], off
	v_lshl_add_u64 v[250:251], v[250:251], 0, s[46:47]
	global_load_dwordx4 v[246:249], v[250:251], off
	v_lshl_add_u64 v[250:251], v[250:251], 0, s[46:47]
	global_load_dwordx4 v[164:167], v[250:251], off
	v_mad_u32_u24 v252, v232, s33, v233
	v_lshlrev_b32_e32 v252, 1, v252
	s_waitcnt vmcnt(0)
	ds_write_b128 v252, v[228:231]
	ds_write_b128 v252, v[242:245] offset:8704
	ds_write_b128 v252, v[246:249] offset:17408
	ds_write_b128 v252, v[164:167] offset:26112
.Lpw_skip3:
	s_branch .LBB0_208
.LBB0_232:
	s_ashr_i32 s0, s90, 6
	v_readlane_b32 s1, v253, 57
	s_add_i32 s4, s0, s1
	v_readlane_b32 s50, v253, 54
	v_readlane_b32 s0, v253, 59
	v_readlane_b32 s54, v253, 38
	v_readlane_b32 s56, v253, 40
	s_cmp_gt_i32 s4, 0xffff
	v_readlane_b32 s51, v253, 55
	v_readlane_b32 s49, v253, 56
	v_readlane_b32 s33, v253, 58
	v_readlane_b32 s44, v254, 9
	v_readlane_b32 s45, v254, 10
	v_readlane_b32 s46, v254, 11
	v_readlane_b32 s47, v254, 12
	s_mov_b32 s48, s0
	v_readlane_b32 s52, v254, 0
	v_readlane_b32 s55, v253, 39
	v_readlane_b32 s57, v253, 41
	v_readlane_b32 s53, v254, 2
	v_readlane_b32 s58, v254, 3
	v_readlane_b32 s59, v254, 4
	s_movk_i32 s60, 0x1000
	v_readlane_b32 s2, v254, 26
	v_readlane_b32 s1, v253, 60
	s_cbranch_scc1 .LBB0_251
	v_readlane_b32 s0, v254, 14
	s_lshl_b32 s0, s2, 8
	s_add_u32 s6, s70, 0x39e00000
	v_readlane_b32 s1, v254, 15
	s_addc_u32 s7, s71, 0
	s_mov_b32 s11, s1
	s_mul_i32 s10, s2, 0x180
	s_add_u32 s8, s70, 0x3a200000
	s_addc_u32 s9, s71, 0
	s_lshl_b64 s[2:3], s[10:11], 2
	s_add_u32 s2, s66, s2
	s_addc_u32 s3, s67, s3
	v_lshlrev_b32_e32 v0, 2, v84
	global_load_dwordx2 v[2:3], v0, s[2:3]
	v_and_b32_e32 v5, 64, v197
	v_add_u32_e32 v6, 64, v5
	v_xor_b32_e32 v5, 1, v197
	v_cmp_lt_i32_e32 vcc, v5, v6
	v_xor_b32_e32 v7, 2, v197
	v_writelane_b32 v254, s0, 14
	v_cndmask_b32_e32 v5, v197, v5, vcc
	v_cmp_lt_i32_e32 vcc, v7, v6
	v_writelane_b32 v254, s1, 15
	s_mov_b32 s1, s11
	v_cndmask_b32_e32 v7, v197, v7, vcc
	v_lshlrev_b32_e32 v42, 2, v7
	v_xor_b32_e32 v7, 4, v197
	v_cmp_lt_i32_e32 vcc, v7, v6
	s_lshl_b64 s[0:1], s[0:1], 2
	v_readlane_b32 s10, v254, 20
	v_cndmask_b32_e32 v7, v197, v7, vcc
	v_lshlrev_b32_e32 v43, 2, v7
	v_xor_b32_e32 v7, 8, v197
	v_cmp_lt_i32_e32 vcc, v7, v6
	v_readlane_b32 s11, v254, 21
	s_add_u32 s10, s10, s0
	v_cndmask_b32_e32 v7, v197, v7, vcc
	v_lshlrev_b32_e32 v44, 2, v7
	v_xor_b32_e32 v7, 16, v197
	v_cmp_lt_i32_e32 vcc, v7, v6
	v_or_b32_e32 v32, 64, v82
	v_or_b32_e32 v34, 0x80, v82
	v_cndmask_b32_e32 v7, v197, v7, vcc
	s_addc_u32 s11, s11, s1
	v_lshlrev_b32_e32 v45, 2, v7
	v_xor_b32_e32 v7, 32, v197
	v_lshlrev_b32_e32 v14, 3, v32
	v_mov_b32_e32 v15, v1
	v_lshlrev_b32_e32 v10, 3, v34
	v_mov_b32_e32 v11, v1
	v_lshl_add_u64 v[12:13], s[10:11], 0, v[0:1]
	v_lshlrev_b32_e32 v0, 2, v82
	v_cmp_lt_i32_e32 vcc, v7, v6
	v_lshl_add_u64 v[8:9], s[2:3], 0, v[14:15]
	v_lshl_add_u64 v[10:11], s[2:3], 0, v[10:11]
	v_lshl_add_u64 v[16:17], s[70:71], 0, v[0:1]
	s_mov_b64 s[2:3], 0x3000000
	s_ashr_i32 s5, s4, 31
	v_and_b32_e32 v4, 15, v118
	v_cndmask_b32_e32 v6, v197, v7, vcc
	v_mov_b32_e32 v85, v1
	v_lshl_add_u64 v[14:15], s[10:11], 0, v[14:15]
	v_lshl_add_u64 v[18:19], v[16:17], 0, s[2:3]
	s_lshl_b64 s[2:3], s[4:5], 6
	s_lshl_b64 s[10:11], s[4:5], 9
	v_lshlrev_b32_e32 v46, 2, v6
	v_lshl_add_u64 v[6:7], s[70:71], 0, v[84:85]
	s_mov_b64 s[12:13], 0x5000000
	v_lshl_add_u64 v[20:21], s[2:3], 0, v[84:85]
	v_or_b32_e32 v22, s10, v0
	s_mul_hi_i32 s5, s4, 0x300
	s_mul_i32 s10, s4, 0x300
	v_lshl_or_b32 v26, v4, 2, s2
	v_mov_b32_e32 v27, s3
	s_mul_hi_i32 s2, s4, 0x1e00
	s_mul_i32 s3, s4, 0x1e00
	v_lshlrev_b32_e32 v5, 2, v5
	v_cmp_gt_u32_e64 s[0:1], 16, v82
	v_lshl_add_u64 v[6:7], v[6:7], 0, s[12:13]
	v_mov_b32_e32 v23, s11
	v_or_b32_e32 v24, s10, v0
	v_mov_b32_e32 v25, s5
	v_or_b32_e32 v28, s3, v0
	v_mov_b32_e32 v29, s2
	v_lshl_or_b32 v30, v4, 1, s3
	v_mov_b32_e32 v31, s2
	v_lshlrev_b32_e32 v47, 2, v82
	v_lshlrev_b32_e32 v48, 2, v32
	v_lshlrev_b32_e32 v49, 2, v34
	s_branch .LBB0_235
